# g3silu + G1o gelu epilogue trims: select via max/sub-abs (no v_cmp), |v| via VOP3 abs modifier; hazard pads restored
# speedup vs baseline: 1.0028x; 1.0028x over previous
; __device__ __forceinline__ unsigned long long f2ss(float v) { return (unsigned long long)(v * 16777216.0f); }
; __device__ __forceinline__ u32x4 pack8(f32x4 v0, f32x4 v1) { u32x4 w; w.x = cvt_pk_bf16(v0[0], v0[1]); w.y = cvt_pk_bf16(v0[2], v0[3]); w.z = cvt_pk_bf16(v1[0], v1[1]); w.w = cvt_pk_bf16(v1[2], v1[3]); return w; }
; __device__ __forceinline__ f32x2 gelu_pk(f32x2 v) {
;     const f32x2 av = __builtin_elementwise_abs(v), d = av * 0.2316418882f + 1.0f;
;     f32x2 t; t.x = __builtin_amdgcn_rcpf(d.x); t.y = __builtin_amdgcn_rcpf(d.y);
;     f32x2 q = t * 0.5307027145f + (-0.7265760135f); q = q * t + 0.7107068705f; q = q * t + (-0.142248368f); q = q * t + 0.127414796f; q = q * t;
;     const f32x2 s = (v * v) * (-0.72134752044f);
;     f32x2 e; e.x = __builtin_amdgcn_exp2f(s.x); e.y = __builtin_amdgcn_exp2f(s.y);
;     const f32x2 m = v * (q * e), r = v - m;
;     f32x2 o; o.x = v.x < 0.f ? m.x : r.x; o.y = v.y < 0.f ? m.y : r.y; return o;
; }
;     __device__ __forceinline__ void operator()(const f32x4 (&acc)[2][2][4][2], const Unit& u, int wr, int wc, int fr, int fq, const Pre& pre) const {
;         const int row0 = u.pm * BM + wr * 64 + fr, col0 = u.pn * BM + wc * 32 + 8 * fq;
;         float rs8[8]; rstd8(rs8, pre, fr);
;         const bool isv = u.pn >= 4;
; #pragma unroll
;         for (int ai = 0; ai < 2; ++ai)
; #pragma unroll
;             for (int m = 0; m < 4; ++m) { const int row = row0 + ai * HALF + m * 16; const float r = rs8[ai * 4 + m];
;                 bf16_t* rowp = O + (size_t)row * 2048 + col0; float sq = 0.f;
; #pragma unroll
;                 for (int bj = 0; bj < 2; ++bj) { f32x4 v0 = acc[ai][bj][m][0] * r, v1 = acc[ai][bj][m][1] * r;
;                     f32x2 a = gelu_pk((f32x2){v0[0], v0[1]}), b = gelu_pk((f32x2){v0[2], v0[3]}), c = gelu_pk((f32x2){v1[0], v1[1]}), d = gelu_pk((f32x2){v1[2], v1[3]});
;                     v0 = (f32x4){a.x, a.y, b.x, b.y}; v1 = (f32x4){c.x, c.y, d.x, d.y};
;                     sq += (v0[0] * v0[0] + v0[1] * v0[1]) + (v0[2] * v0[2] + v0[3] * v0[3]) + (v1[0] * v1[0] + v1[1] * v1[1]) + (v1[2] * v1[2] + v1[3] * v1[3]);
;                     *(u32x4*)(rowp + bj * HALF) = pack8(v0, v1); }
;                 if (isv) { sq += __shfl_xor(sq, 16); sq += __shfl_xor(sq, 32); if (fq == 0) atomicAdd(vss + row, f2ss(sq)); } }
.LBB0_57:
	s_waitcnt vmcnt(8)
	v_ffbh_u32_e32 v154, v153
	v_min_u32_e32 v154, 32, v154
	v_lshlrev_b64 v[152:153], v154, v[152:153]
	v_min_u32_e32 v152, 1, v152
	v_or_b32_e32 v152, v153, v152
	v_cvt_f32_u32_e32 v152, v152
	v_sub_u32_e32 v153, 32, v154
	s_mov_b32 s8, 0x3e6d3388
	s_cmp_gt_i32 s4, 3
	v_ldexp_f32 v152, v152, v153
	v_ffbh_u32_e32 v153, v147
	v_min_u32_e32 v153, 32, v153
	v_lshlrev_b64 v[146:147], v153, v[146:147]
	v_min_u32_e32 v146, 1, v146
	v_or_b32_e32 v146, v147, v146
	v_cvt_f32_u32_e32 v146, v146
	v_mul_f32_e32 v152, 0x33800000, v152
	v_fmamk_f32 v152, v152, 0x3a800000, v233
	v_rsq_f32_e32 v152, v152
	v_sub_u32_e32 v147, 32, v153
	v_ldexp_f32 v146, v146, v147
	v_and_b32_e32 v147, 64, v236
	v_or_b32_e32 v153, v147, v145
	v_lshlrev_b32_e32 v153, 2, v153
	ds_bpermute_b32 v168, v153, v152
	v_mul_f32_e32 v146, 0x33800000, v146
	v_fmamk_f32 v146, v146, 0x3a800000, v233
	v_rsq_f32_e32 v146, v146
	s_mov_b32 s12, 0xbf3a00e3
	s_waitcnt lgkmcnt(0)
	v_pk_mul_f32 v[124:125], v[124:125], v[168:169] op_sel_hi:[1,0]
	v_pk_mul_f32 v[170:171], v[120:121], v[168:169] op_sel_hi:[1,0]
	v_fma_f32 v120, |v124|, s8, 1.0
	v_fma_f32 v121, |v125|, s8, 1.0
	v_lshl_or_b32 v162, s4, 8, v159
	v_rcp_f32_e32 v172, v120
	v_rcp_f32_e32 v173, v121
	s_cselect_b64 s[64:65], -1, 0
	s_cmp_lt_i32 s4, 4
	v_mov_b64_e32 v[120:121], s[12:13]
	s_mov_b32 s10, 0x3f07dc22
	v_pk_mul_f32 v[176:177], v[124:125], v[124:125]
	s_mov_b32 s4, 0xbf38aa3b
	v_pk_fma_f32 v[174:175], v[172:173], s[10:11], v[120:121] op_sel_hi:[1,0,0]
	s_mov_b32 s14, 0x3f35f0e3
	v_pk_mul_f32 v[176:177], v[176:177], s[4:5] op_sel_hi:[1,0]
	v_pk_fma_f32 v[174:175], v[172:173], v[174:175], s[14:15] op_sel_hi:[1,1,0]
	s_mov_b32 s36, 0xbe11a98e
	v_exp_f32_e32 v176, v176
	v_exp_f32_e32 v177, v177
	ds_bpermute_b32 v166, v153, v146
	ds_bpermute_b32 v164, v153, v152 offset:64
	ds_bpermute_b32 v160, v153, v146 offset:64
	ds_bpermute_b32 v158, v153, v152 offset:128
	ds_bpermute_b32 v156, v153, v146 offset:128
	ds_bpermute_b32 v154, v153, v152 offset:192
	ds_bpermute_b32 v146, v153, v146 offset:192
	v_xor_b32_e32 v152, 16, v236
	v_add_u32_e32 v153, 64, v147
	v_pk_fma_f32 v[174:175], v[172:173], v[174:175], s[36:37] op_sel_hi:[1,1,0]
	s_mov_b32 s66, 0x3e027906
	v_cmp_lt_i32_e32 vcc, v152, v153
	v_pk_fma_f32 v[174:175], v[172:173], v[174:175], s[66:67] op_sel_hi:[1,1,0]
	v_pk_mul_f32 v[126:127], v[126:127], v[168:169] op_sel_hi:[1,0]
	v_cndmask_b32_e32 v147, v236, v152, vcc
	v_xor_b32_e32 v152, 32, v236
	v_pk_mul_f32 v[172:173], v[172:173], v[174:175]
	v_cmp_lt_i32_e32 vcc, v152, v153
	v_pk_mul_f32 v[172:173], v[176:177], v[172:173]
	v_pk_mul_f32 v[174:175], v[126:127], v[126:127]
	v_cndmask_b32_e32 v152, v236, v152, vcc
	v_pk_mul_f32 v[176:177], v[124:125], v[172:173]
	v_max_f32_e32 v172, 0, v124
	v_max_f32_e32 v173, 0, v125
	v_pk_mul_f32 v[174:175], v[174:175], s[4:5] op_sel_hi:[1,0]
	v_pk_mul_f32 v[122:123], v[122:123], v[168:169] op_sel_hi:[1,0]
	v_sub_f32_e64 v124, v172, |v176|
	v_exp_f32_e32 v174, v174
	v_sub_f32_e64 v125, v173, |v177|
	v_fma_f32 v172, |v126|, s8, 1.0
	v_fma_f32 v173, |v127|, s8, 1.0
	v_exp_f32_e32 v175, v175
	v_rcp_f32_e32 v172, v172
	v_rcp_f32_e32 v173, v173
	v_lshlrev_b32_e32 v165, 2, v152
	v_lshlrev_b64 v[152:153], 12, v[142:143]
	v_pk_fma_f32 v[176:177], v[172:173], s[10:11], v[120:121] op_sel_hi:[1,0,0]
	v_ashrrev_i32_e32 v163, 31, v162
	v_pk_fma_f32 v[176:177], v[172:173], v[176:177], s[14:15] op_sel_hi:[1,1,0]
	v_lshl_add_u64 v[152:153], s[30:31], 0, v[152:153]
	v_pk_fma_f32 v[176:177], v[172:173], v[176:177], s[36:37] op_sel_hi:[1,1,0]
	v_lshl_add_u64 v[152:153], v[162:163], 1, v[152:153]
	v_pk_fma_f32 v[176:177], v[172:173], v[176:177], s[66:67] op_sel_hi:[1,1,0]
	v_lshlrev_b32_e32 v147, 2, v147
	v_pk_mul_f32 v[172:173], v[172:173], v[176:177]
	v_pk_mul_f32 v[176:177], v[170:171], v[170:171]
	v_pk_mul_f32 v[172:173], v[174:175], v[172:173]
	v_pk_mul_f32 v[176:177], v[176:177], s[4:5] op_sel_hi:[1,0]
	v_pk_mul_f32 v[174:175], v[126:127], v[172:173]
	v_max_f32_e32 v172, 0, v126
	v_max_f32_e32 v173, 0, v127
	v_exp_f32_e32 v176, v176
	v_sub_f32_e64 v126, v172, |v174|
	v_exp_f32_e32 v177, v177
	v_sub_f32_e64 v127, v173, |v175|
	v_fma_f32 v172, |v170|, s8, 1.0
	v_fma_f32 v173, |v171|, s8, 1.0
	v_rcp_f32_e32 v172, v172
	v_rcp_f32_e32 v173, v173
	v_readlane_b32 s76, v255, 14
	v_readlane_b32 s77, v255, 15
	v_pk_fma_f32 v[174:175], v[172:173], s[10:11], v[120:121] op_sel_hi:[1,0,0]
	s_nop 0
	v_pk_fma_f32 v[174:175], v[172:173], v[174:175], s[14:15] op_sel_hi:[1,1,0]
	s_nop 0
	v_pk_fma_f32 v[174:175], v[172:173], v[174:175], s[36:37] op_sel_hi:[1,1,0]
	s_nop 0
	v_pk_fma_f32 v[174:175], v[172:173], v[174:175], s[66:67] op_sel_hi:[1,1,0]
	s_nop 0
	v_pk_mul_f32 v[172:173], v[172:173], v[174:175]
	v_pk_mul_f32 v[174:175], v[122:123], v[122:123]
	v_pk_mul_f32 v[172:173], v[176:177], v[172:173]
	s_nop 0
	v_pk_mul_f32 v[176:177], v[170:171], v[172:173]
	v_max_f32_e32 v172, 0, v170
	v_max_f32_e32 v173, 0, v171
	v_sub_f32_e64 v167, v172, |v176|
	v_fma_f32 v170, |v122|, s8, 1.0
	v_fma_f32 v171, |v123|, s8, 1.0
	v_sub_f32_e64 v169, v173, |v177|
	v_rcp_f32_e32 v170, v170
	v_rcp_f32_e32 v171, v171
	v_pk_mul_f32 v[116:117], v[116:117], v[168:169] op_sel_hi:[1,0]
	v_pk_mul_f32 v[118:119], v[118:119], v[168:169] op_sel_hi:[1,0]
	v_pk_fma_f32 v[172:173], v[170:171], s[10:11], v[120:121] op_sel_hi:[1,0,0]
	v_pk_mul_f32 v[114:115], v[114:115], v[168:169] op_sel_hi:[1,0]
	v_pk_fma_f32 v[172:173], v[170:171], v[172:173], s[14:15] op_sel_hi:[1,1,0]
	s_nop 0
	v_pk_fma_f32 v[172:173], v[170:171], v[172:173], s[36:37] op_sel_hi:[1,1,0]
	s_nop 0
	v_pk_fma_f32 v[172:173], v[170:171], v[172:173], s[66:67] op_sel_hi:[1,1,0]
; __device__ __forceinline__ unsigned long long f2ss(float v) { return (unsigned long long)(v * 16777216.0f); }
; __device__ __forceinline__ u32x4 pack8(f32x4 v0, f32x4 v1) { u32x4 w; w.x = cvt_pk_bf16(v0[0], v0[1]); w.y = cvt_pk_bf16(v0[2], v0[3]); w.z = cvt_pk_bf16(v1[0], v1[1]); w.w = cvt_pk_bf16(v1[2], v1[3]); return w; }
; __device__ __forceinline__ f32x2 gelu_pk(f32x2 v) {
;     const f32x2 av = __builtin_elementwise_abs(v), d = av * 0.2316418882f + 1.0f;
;     f32x2 t; t.x = __builtin_amdgcn_rcpf(d.x); t.y = __builtin_amdgcn_rcpf(d.y);
;     f32x2 q = t * 0.5307027145f + (-0.7265760135f); q = q * t + 0.7107068705f; q = q * t + (-0.142248368f); q = q * t + 0.127414796f; q = q * t;
;     const f32x2 s = (v * v) * (-0.72134752044f);
;     f32x2 e; e.x = __builtin_amdgcn_exp2f(s.x); e.y = __builtin_amdgcn_exp2f(s.y);
;     const f32x2 m = v * (q * e), r = v - m;
;     f32x2 o; o.x = v.x < 0.f ? m.x : r.x; o.y = v.y < 0.f ? m.y : r.y; return o;
; }
;     __device__ __forceinline__ void operator()(const f32x4 (&acc)[2][2][4][2], const Unit& u, int wr, int wc, int fr, int fq, const Pre& pre) const {
;     ...
;             for (int m = 0; m < 4; ++m) { const int row = row0 + ai * HALF + m * 16; const float r = rs8[ai * 4 + m];
;                 bf16_t* rowp = O + (size_t)row * 2048 + col0; float sq = 0.f;
; #pragma unroll
;                 for (int bj = 0; bj < 2; ++bj) { f32x4 v0 = acc[ai][bj][m][0] * r, v1 = acc[ai][bj][m][1] * r;
;                     f32x2 a = gelu_pk((f32x2){v0[0], v0[1]}), b = gelu_pk((f32x2){v0[2], v0[3]}), c = gelu_pk((f32x2){v1[0], v1[1]}), d = gelu_pk((f32x2){v1[2], v1[3]});
;                     v0 = (f32x4){a.x, a.y, b.x, b.y}; v1 = (f32x4){c.x, c.y, d.x, d.y};
;                     sq += (v0[0] * v0[0] + v0[1] * v0[1]) + (v0[2] * v0[2] + v0[3] * v0[3]) + (v1[0] * v1[0] + v1[1] * v1[1]) + (v1[2] * v1[2] + v1[3] * v1[3]);
;                     *(u32x4*)(rowp + bj * HALF) = pack8(v0, v1); }
;                 if (isv) { sq += __shfl_xor(sq, 16); sq += __shfl_xor(sq, 32); if (fq == 0) atomicAdd(vss + row, f2ss(sq)); } }
	s_nop 0
	v_pk_mul_f32 v[170:171], v[170:171], v[172:173]
	v_pk_mul_f32 v[172:173], v[174:175], s[4:5] op_sel_hi:[1,0]
	v_pk_mul_f32 v[174:175], v[116:117], v[116:117]
	v_exp_f32_e32 v172, v172
	v_exp_f32_e32 v173, v173
	v_pk_mul_f32 v[174:175], v[174:175], s[4:5] op_sel_hi:[1,0]
	v_pk_mul_f32 v[170:171], v[172:173], v[170:171]
	s_nop 0
	v_pk_mul_f32 v[172:173], v[122:123], v[170:171]
	v_max_f32_e32 v170, 0, v122
	v_max_f32_e32 v171, 0, v123
	v_exp_f32_e32 v174, v174
	v_sub_f32_e64 v122, v170, |v172|
	v_cvt_pk_bf16_f32 v170, v124, v125
	v_exp_f32_e32 v175, v175
	s_nop 0
	v_sub_f32_e64 v123, v171, |v173|
	v_cvt_pk_bf16_f32 v171, v126, v127
	v_cvt_pk_bf16_f32 v172, v167, v169
	v_cvt_pk_bf16_f32 v173, v122, v123
	global_store_dwordx4 v[152:153], v[170:173], off nt
	s_nop 0
	s_nop 0
	v_pk_mul_f32 v[170:171], v[112:113], v[168:169] op_sel_hi:[1,0]
	v_fma_f32 v112, |v116|, s8, 1.0
	v_fma_f32 v113, |v117|, s8, 1.0
	s_nop 0
	v_rcp_f32_e32 v112, v112
	v_rcp_f32_e32 v113, v113
	s_nop 0
	v_pk_fma_f32 v[172:173], v[112:113], s[10:11], v[120:121] op_sel_hi:[1,0,0]
	s_nop 0
	v_pk_fma_f32 v[172:173], v[112:113], v[172:173], s[14:15] op_sel_hi:[1,1,0]
	s_nop 0
	v_pk_fma_f32 v[172:173], v[112:113], v[172:173], s[36:37] op_sel_hi:[1,1,0]
	s_nop 0
	v_pk_fma_f32 v[172:173], v[112:113], v[172:173], s[66:67] op_sel_hi:[1,1,0]
	s_nop 0
	v_pk_mul_f32 v[112:113], v[112:113], v[172:173]
	v_pk_mul_f32 v[172:173], v[118:119], v[118:119]
	v_pk_mul_f32 v[112:113], v[174:175], v[112:113]
	v_pk_mul_f32 v[172:173], v[172:173], s[4:5] op_sel_hi:[1,0]
	v_pk_mul_f32 v[174:175], v[116:117], v[112:113]
	v_max_f32_e32 v112, 0, v116
	v_max_f32_e32 v113, 0, v117
	v_sub_f32_e64 v112, v112, |v174|
	v_fma_f32 v116, |v118|, s8, 1.0
	v_fma_f32 v117, |v119|, s8, 1.0
	v_sub_f32_e64 v113, v113, |v175|
	v_rcp_f32_e32 v116, v116
	v_rcp_f32_e32 v117, v117
	v_exp_f32_e32 v172, v172
	v_exp_f32_e32 v173, v173
	v_pk_fma_f32 v[174:175], v[116:117], s[10:11], v[120:121] op_sel_hi:[1,0,0]
	s_nop 0
	v_pk_fma_f32 v[174:175], v[116:117], v[174:175], s[14:15] op_sel_hi:[1,1,0]
	s_nop 0
	v_pk_fma_f32 v[174:175], v[116:117], v[174:175], s[36:37] op_sel_hi:[1,1,0]
	s_nop 0
	v_pk_fma_f32 v[174:175], v[116:117], v[174:175], s[66:67] op_sel_hi:[1,1,0]
	s_nop 0
	v_pk_mul_f32 v[116:117], v[116:117], v[174:175]
	v_pk_mul_f32 v[174:175], v[170:171], v[170:171]
	v_pk_mul_f32 v[116:117], v[172:173], v[116:117]
	v_pk_mul_f32 v[174:175], v[174:175], s[4:5] op_sel_hi:[1,0]
	v_pk_mul_f32 v[172:173], v[118:119], v[116:117]
	v_max_f32_e32 v116, 0, v118
	v_max_f32_e32 v117, 0, v119
	v_sub_f32_e64 v116, v116, |v172|
	v_fma_f32 v118, |v170|, s8, 1.0
	v_fma_f32 v119, |v171|, s8, 1.0
	v_sub_f32_e64 v117, v117, |v173|
	v_rcp_f32_e32 v118, v118
	v_rcp_f32_e32 v119, v119
	v_exp_f32_e32 v174, v174
	v_exp_f32_e32 v175, v175
	v_pk_fma_f32 v[172:173], v[118:119], s[10:11], v[120:121] op_sel_hi:[1,0,0]
	s_nop 0
	v_pk_fma_f32 v[172:173], v[118:119], v[172:173], s[14:15] op_sel_hi:[1,1,0]
	s_nop 0
	v_pk_fma_f32 v[172:173], v[118:119], v[172:173], s[36:37] op_sel_hi:[1,1,0]
	s_nop 0
	v_pk_fma_f32 v[172:173], v[118:119], v[172:173], s[66:67] op_sel_hi:[1,1,0]
	s_nop 0
	v_pk_mul_f32 v[118:119], v[118:119], v[172:173]
	v_pk_mul_f32 v[172:173], v[114:115], v[114:115]
	v_pk_mul_f32 v[118:119], v[174:175], v[118:119]
	s_nop 0
	v_pk_mul_f32 v[174:175], v[170:171], v[118:119]
	v_max_f32_e32 v118, 0, v170
	v_max_f32_e32 v119, 0, v171
	v_sub_f32_e64 v118, v118, |v174|
	v_fma_f32 v170, |v114|, s8, 1.0
	v_fma_f32 v171, |v115|, s8, 1.0
	v_sub_f32_e64 v119, v119, |v175|
	v_rcp_f32_e32 v170, v170
	v_rcp_f32_e32 v171, v171
	s_nop 0
	v_pk_fma_f32 v[120:121], v[170:171], s[10:11], v[120:121] op_sel_hi:[1,0,0]
	s_nop 0
	v_pk_fma_f32 v[120:121], v[170:171], v[120:121], s[14:15] op_sel_hi:[1,1,0]
	s_nop 0
	v_pk_fma_f32 v[120:121], v[170:171], v[120:121], s[36:37] op_sel_hi:[1,1,0]
	s_nop 0
	v_pk_fma_f32 v[120:121], v[170:171], v[120:121], s[66:67] op_sel_hi:[1,1,0]
	s_nop 0
	v_pk_mul_f32 v[120:121], v[170:171], v[120:121]
	v_pk_mul_f32 v[170:171], v[172:173], s[4:5] op_sel_hi:[1,0]
	s_nop 0
	v_exp_f32_e32 v170, v170
	v_exp_f32_e32 v171, v171
	s_nop 0
	v_pk_mul_f32 v[120:121], v[170:171], v[120:121]
	s_nop 0
	v_pk_mul_f32 v[170:171], v[114:115], v[120:121]
	v_max_f32_e32 v120, 0, v114
	v_max_f32_e32 v121, 0, v115
	s_nop 0
	v_sub_f32_e64 v114, v120, |v170|
	v_cvt_pk_bf16_f32 v170, v112, v113
	s_nop 1
	v_sub_f32_e64 v115, v121, |v171|
	v_cvt_pk_bf16_f32 v171, v116, v117
	v_cvt_pk_bf16_f32 v172, v118, v119
	v_cvt_pk_bf16_f32 v173, v114, v115
	global_store_dwordx4 v[152:153], v[170:173], off offset:256 nt
	s_cbranch_scc1 .LBB0_61
	v_mul_f32_e32 v120, v123, v123
	v_mul_f32_e32 v113, v113, v113
	v_fmac_f32_e32 v120, v122, v122
	v_mul_f32_e32 v121, v125, v125
	v_mul_f32_e32 v122, v127, v127
	v_fmac_f32_e32 v113, v112, v112
	v_mul_f32_e32 v112, v117, v117
	v_fmac_f32_e32 v121, v124, v124
	v_fmac_f32_e32 v122, v126, v126
	v_fmac_f32_e32 v112, v116, v116
	v_add_f32_e32 v121, v121, v122
	v_mul_f32_e32 v122, v169, v169
	v_add_f32_e32 v112, v113, v112
	v_mul_f32_e32 v113, v119, v119
	v_fmac_f32_e32 v122, v167, v167
	v_mul_f32_e32 v115, v115, v115
	v_fmac_f32_e32 v113, v118, v118
	v_add_f32_e32 v121, v122, v121
	v_fmac_f32_e32 v115, v114, v114
	v_add_f32_e32 v112, v113, v112
	v_add_f32_e32 v120, v120, v121
	v_add_f32_e32 v112, v115, v112
	v_add_f32_e32 v112, v120, v112
	ds_bpermute_b32 v113, v147, v112
	s_waitcnt lgkmcnt(0)
	v_add_f32_e32 v112, v112, v113
	ds_bpermute_b32 v113, v165, v112
	s_and_saveexec_b64 s[26:27], s[40:41]
	s_cbranch_execz .LBB0_60
	s_waitcnt lgkmcnt(0)
	v_add_f32_e32 v112, v112, v113
	v_mul_f32_e32 v112, 0x4b800000, v112
	v_trunc_f32_e32 v112, v112
	v_mul_f32_e32 v113, 0x2f800000, v112
	v_floor_f32_e32 v113, v113
	v_fmac_f32_e32 v112, 0xcf800000, v113
	v_cvt_u32_f32_e32 v112, v112
	v_cvt_u32_f32_e32 v113, v113
	v_lshl_add_u64 v[114:115], v[142:143], 3, s[52:53]
	global_atomic_add_x2 v[114:115], v[112:113], off

; __device__ __forceinline__ unsigned long long f2ss(float v) { return (unsigned long long)(v * 16777216.0f); }
; __device__ __forceinline__ u32x4 pack8(f32x4 v0, f32x4 v1) { u32x4 w; w.x = cvt_pk_bf16(v0[0], v0[1]); w.y = cvt_pk_bf16(v0[2], v0[3]); w.z = cvt_pk_bf16(v1[0], v1[1]); w.w = cvt_pk_bf16(v1[2], v1[3]); return w; }
; __device__ __forceinline__ f32x2 gelu_pk(f32x2 v) {
;     const f32x2 av = __builtin_elementwise_abs(v), d = av * 0.2316418882f + 1.0f;
;     f32x2 t; t.x = __builtin_amdgcn_rcpf(d.x); t.y = __builtin_amdgcn_rcpf(d.y);
;     f32x2 q = t * 0.5307027145f + (-0.7265760135f); q = q * t + 0.7107068705f; q = q * t + (-0.142248368f); q = q * t + 0.127414796f; q = q * t;
;     const f32x2 s = (v * v) * (-0.72134752044f);
;     f32x2 e; e.x = __builtin_amdgcn_exp2f(s.x); e.y = __builtin_amdgcn_exp2f(s.y);
;     const f32x2 m = v * (q * e), r = v - m;
;     f32x2 o; o.x = v.x < 0.f ? m.x : r.x; o.y = v.y < 0.f ? m.y : r.y; return o;
; }
;     __device__ __forceinline__ void operator()(const f32x4 (&acc)[2][2][4][2], const Unit& u, int wr, int wc, int fr, int fq, const Pre& pre) const {
;     ...
;             for (int m = 0; m < 4; ++m) { const int row = row0 + ai * HALF + m * 16; const float r = rs8[ai * 4 + m];
;                 bf16_t* rowp = O + (size_t)row * 2048 + col0; float sq = 0.f;
; #pragma unroll
;                 for (int bj = 0; bj < 2; ++bj) { f32x4 v0 = acc[ai][bj][m][0] * r, v1 = acc[ai][bj][m][1] * r;
;                     f32x2 a = gelu_pk((f32x2){v0[0], v0[1]}), b = gelu_pk((f32x2){v0[2], v0[3]}), c = gelu_pk((f32x2){v1[0], v1[1]}), d = gelu_pk((f32x2){v1[2], v1[3]});
;                     v0 = (f32x4){a.x, a.y, b.x, b.y}; v1 = (f32x4){c.x, c.y, d.x, d.y};
;                     sq += (v0[0] * v0[0] + v0[1] * v0[1]) + (v0[2] * v0[2] + v0[3] * v0[3]) + (v1[0] * v1[0] + v1[1] * v1[1]) + (v1[2] * v1[2] + v1[3] * v1[3]);
;                     *(u32x4*)(rowp + bj * HALF) = pack8(v0, v1); }
;                 if (isv) { sq += __shfl_xor(sq, 16); sq += __shfl_xor(sq, 32); if (fq == 0) atomicAdd(vss + row, f2ss(sq)); } }
.LBB0_61:
	s_waitcnt lgkmcnt(0)
	v_pk_mul_f32 v[108:109], v[108:109], v[166:167] op_sel_hi:[1,0]
	v_pk_mul_f32 v[114:115], v[104:105], v[166:167] op_sel_hi:[1,0]
	v_fma_f32 v104, |v108|, s8, 1.0
	v_fma_f32 v105, |v109|, s8, 1.0
	v_pk_mul_f32 v[120:121], v[108:109], v[108:109]
	v_rcp_f32_e32 v116, v104
	v_rcp_f32_e32 v117, v105
	v_mov_b64_e32 v[104:105], s[12:13]
	v_pk_mul_f32 v[120:121], v[120:121], s[4:5] op_sel_hi:[1,0]
	v_pk_fma_f32 v[118:119], v[116:117], s[10:11], v[104:105] op_sel_hi:[1,0,0]
	v_exp_f32_e32 v120, v120
	v_pk_fma_f32 v[118:119], v[116:117], v[118:119], s[14:15] op_sel_hi:[1,1,0]
	v_exp_f32_e32 v121, v121
	v_pk_fma_f32 v[118:119], v[116:117], v[118:119], s[36:37] op_sel_hi:[1,1,0]
	v_pk_mul_f32 v[110:111], v[110:111], v[166:167] op_sel_hi:[1,0]
	v_pk_fma_f32 v[118:119], v[116:117], v[118:119], s[66:67] op_sel_hi:[1,1,0]
	v_pk_mul_f32 v[106:107], v[106:107], v[166:167] op_sel_hi:[1,0]
	v_pk_mul_f32 v[116:117], v[116:117], v[118:119]
	v_pk_mul_f32 v[118:119], v[110:111], v[110:111]
	v_pk_mul_f32 v[116:117], v[120:121], v[116:117]
	v_pk_mul_f32 v[118:119], v[118:119], s[4:5] op_sel_hi:[1,0]
	v_pk_mul_f32 v[120:121], v[108:109], v[116:117]
	v_max_f32_e32 v116, 0, v108
	v_max_f32_e32 v117, 0, v109
	v_exp_f32_e32 v118, v118
	v_sub_f32_e64 v108, v116, |v120|
	v_exp_f32_e32 v119, v119
	v_sub_f32_e64 v109, v117, |v121|
	v_fma_f32 v116, |v110|, s8, 1.0
	v_fma_f32 v117, |v111|, s8, 1.0
	v_rcp_f32_e32 v116, v116
	v_rcp_f32_e32 v117, v117
	v_or_b32_e32 v112, 16, v142
	v_ashrrev_i32_e32 v113, 31, v112
	v_lshlrev_b64 v[112:113], 12, v[112:113]
	v_pk_fma_f32 v[120:121], v[116:117], s[10:11], v[104:105] op_sel_hi:[1,0,0]
	v_lshl_add_u64 v[112:113], s[30:31], 0, v[112:113]
	v_pk_fma_f32 v[120:121], v[116:117], v[120:121], s[14:15] op_sel_hi:[1,1,0]
	v_lshl_add_u64 v[112:113], v[162:163], 1, v[112:113]
	v_pk_fma_f32 v[120:121], v[116:117], v[120:121], s[36:37] op_sel_hi:[1,1,0]
	v_pk_mul_f32 v[100:101], v[100:101], v[166:167] op_sel_hi:[1,0]
	v_pk_fma_f32 v[120:121], v[116:117], v[120:121], s[66:67] op_sel_hi:[1,1,0]
	v_pk_mul_f32 v[102:103], v[102:103], v[166:167] op_sel_hi:[1,0]
	v_pk_mul_f32 v[116:117], v[116:117], v[120:121]
	v_pk_mul_f32 v[120:121], v[114:115], v[114:115]
	v_pk_mul_f32 v[116:117], v[118:119], v[116:117]
	v_pk_mul_f32 v[120:121], v[120:121], s[4:5] op_sel_hi:[1,0]
	v_pk_mul_f32 v[118:119], v[110:111], v[116:117]
	v_max_f32_e32 v116, 0, v110
	v_max_f32_e32 v117, 0, v111
	v_exp_f32_e32 v120, v120
	v_sub_f32_e64 v110, v116, |v118|
	v_exp_f32_e32 v121, v121
	v_sub_f32_e64 v111, v117, |v119|
	v_fma_f32 v116, |v114|, s8, 1.0
	v_fma_f32 v117, |v115|, s8, 1.0
	v_rcp_f32_e32 v116, v116
	v_rcp_f32_e32 v117, v117
	v_pk_mul_f32 v[98:99], v[98:99], v[166:167] op_sel_hi:[1,0]
	v_pk_fma_f32 v[118:119], v[116:117], s[10:11], v[104:105] op_sel_hi:[1,0,0]
	s_nop 0
	v_pk_fma_f32 v[118:119], v[116:117], v[118:119], s[14:15] op_sel_hi:[1,1,0]
	s_nop 0
	v_pk_fma_f32 v[118:119], v[116:117], v[118:119], s[36:37] op_sel_hi:[1,1,0]
	s_nop 0
	v_pk_fma_f32 v[118:119], v[116:117], v[118:119], s[66:67] op_sel_hi:[1,1,0]
	s_nop 0
	v_pk_mul_f32 v[116:117], v[116:117], v[118:119]
	v_pk_mul_f32 v[118:119], v[106:107], v[106:107]
	v_pk_mul_f32 v[116:117], v[120:121], v[116:117]
	v_pk_mul_f32 v[118:119], v[118:119], s[4:5] op_sel_hi:[1,0]
	v_pk_mul_f32 v[120:121], v[114:115], v[116:117]
	v_max_f32_e32 v116, 0, v114
	v_max_f32_e32 v117, 0, v115
	v_exp_f32_e32 v118, v118
	v_sub_f32_e64 v114, v116, |v120|
	v_exp_f32_e32 v119, v119
	v_sub_f32_e64 v115, v117, |v121|
	v_fma_f32 v116, |v106|, s8, 1.0
	v_fma_f32 v117, |v107|, s8, 1.0
	v_rcp_f32_e32 v116, v116
	v_rcp_f32_e32 v117, v117
	s_nop 0
	v_pk_fma_f32 v[120:121], v[116:117], s[10:11], v[104:105] op_sel_hi:[1,0,0]
	s_nop 0
	v_pk_fma_f32 v[120:121], v[116:117], v[120:121], s[14:15] op_sel_hi:[1,1,0]
	s_nop 0
	v_pk_fma_f32 v[120:121], v[116:117], v[120:121], s[36:37] op_sel_hi:[1,1,0]
	s_nop 0
	v_pk_fma_f32 v[120:121], v[116:117], v[120:121], s[66:67] op_sel_hi:[1,1,0]
	s_nop 0
	v_pk_mul_f32 v[116:117], v[116:117], v[120:121]
	v_pk_mul_f32 v[120:121], v[100:101], v[100:101]
	v_pk_mul_f32 v[116:117], v[118:119], v[116:117]
	v_pk_mul_f32 v[120:121], v[120:121], s[4:5] op_sel_hi:[1,0]
	v_pk_mul_f32 v[118:119], v[106:107], v[116:117]
	v_max_f32_e32 v116, 0, v106
	v_max_f32_e32 v117, 0, v107
	v_exp_f32_e32 v120, v120
	v_sub_f32_e64 v106, v116, |v118|
	v_cvt_pk_bf16_f32 v116, v108, v109
	v_exp_f32_e32 v121, v121
	s_nop 0
	v_sub_f32_e64 v107, v117, |v119|
	v_cvt_pk_bf16_f32 v117, v110, v111
	v_cvt_pk_bf16_f32 v118, v114, v115
	v_cvt_pk_bf16_f32 v119, v106, v107
	global_store_dwordx4 v[112:113], v[116:119], off nt
	s_nop 0
	s_nop 0
	v_pk_mul_f32 v[116:117], v[96:97], v[166:167] op_sel_hi:[1,0]
	v_fma_f32 v96, |v100|, s8, 1.0
	v_fma_f32 v97, |v101|, s8, 1.0
	s_nop 0
	v_rcp_f32_e32 v96, v96
	v_rcp_f32_e32 v97, v97
	s_nop 0
	v_pk_fma_f32 v[118:119], v[96:97], s[10:11], v[104:105] op_sel_hi:[1,0,0]
; __device__ __forceinline__ unsigned long long f2ss(float v) { return (unsigned long long)(v * 16777216.0f); }
; __device__ __forceinline__ u32x4 pack8(f32x4 v0, f32x4 v1) { u32x4 w; w.x = cvt_pk_bf16(v0[0], v0[1]); w.y = cvt_pk_bf16(v0[2], v0[3]); w.z = cvt_pk_bf16(v1[0], v1[1]); w.w = cvt_pk_bf16(v1[2], v1[3]); return w; }
; __device__ __forceinline__ f32x2 gelu_pk(f32x2 v) {
;     const f32x2 av = __builtin_elementwise_abs(v), d = av * 0.2316418882f + 1.0f;
;     f32x2 t; t.x = __builtin_amdgcn_rcpf(d.x); t.y = __builtin_amdgcn_rcpf(d.y);
;     f32x2 q = t * 0.5307027145f + (-0.7265760135f); q = q * t + 0.7107068705f; q = q * t + (-0.142248368f); q = q * t + 0.127414796f; q = q * t;
;     const f32x2 s = (v * v) * (-0.72134752044f);
;     f32x2 e; e.x = __builtin_amdgcn_exp2f(s.x); e.y = __builtin_amdgcn_exp2f(s.y);
;     const f32x2 m = v * (q * e), r = v - m;
;     f32x2 o; o.x = v.x < 0.f ? m.x : r.x; o.y = v.y < 0.f ? m.y : r.y; return o;
; }
;     __device__ __forceinline__ void operator()(const f32x4 (&acc)[2][2][4][2], const Unit& u, int wr, int wc, int fr, int fq, const Pre& pre) const {
;     ...
;             for (int m = 0; m < 4; ++m) { const int row = row0 + ai * HALF + m * 16; const float r = rs8[ai * 4 + m];
;                 bf16_t* rowp = O + (size_t)row * 2048 + col0; float sq = 0.f;
; #pragma unroll
;                 for (int bj = 0; bj < 2; ++bj) { f32x4 v0 = acc[ai][bj][m][0] * r, v1 = acc[ai][bj][m][1] * r;
;                     f32x2 a = gelu_pk((f32x2){v0[0], v0[1]}), b = gelu_pk((f32x2){v0[2], v0[3]}), c = gelu_pk((f32x2){v1[0], v1[1]}), d = gelu_pk((f32x2){v1[2], v1[3]});
;                     v0 = (f32x4){a.x, a.y, b.x, b.y}; v1 = (f32x4){c.x, c.y, d.x, d.y};
;                     sq += (v0[0] * v0[0] + v0[1] * v0[1]) + (v0[2] * v0[2] + v0[3] * v0[3]) + (v1[0] * v1[0] + v1[1] * v1[1]) + (v1[2] * v1[2] + v1[3] * v1[3]);
;                     *(u32x4*)(rowp + bj * HALF) = pack8(v0, v1); }
;                 if (isv) { sq += __shfl_xor(sq, 16); sq += __shfl_xor(sq, 32); if (fq == 0) atomicAdd(vss + row, f2ss(sq)); } }
	s_nop 0
	v_pk_fma_f32 v[118:119], v[96:97], v[118:119], s[14:15] op_sel_hi:[1,1,0]
	s_nop 0
	v_pk_fma_f32 v[118:119], v[96:97], v[118:119], s[36:37] op_sel_hi:[1,1,0]
	s_nop 0
	v_pk_fma_f32 v[118:119], v[96:97], v[118:119], s[66:67] op_sel_hi:[1,1,0]
	s_nop 0
	v_pk_mul_f32 v[96:97], v[96:97], v[118:119]
	v_pk_mul_f32 v[118:119], v[102:103], v[102:103]
	v_pk_mul_f32 v[96:97], v[120:121], v[96:97]
	v_pk_mul_f32 v[118:119], v[118:119], s[4:5] op_sel_hi:[1,0]
	v_pk_mul_f32 v[120:121], v[100:101], v[96:97]
	v_max_f32_e32 v96, 0, v100
	v_max_f32_e32 v97, 0, v101
	v_sub_f32_e64 v96, v96, |v120|
	v_fma_f32 v100, |v102|, s8, 1.0
	v_fma_f32 v101, |v103|, s8, 1.0
	v_sub_f32_e64 v97, v97, |v121|
	v_rcp_f32_e32 v100, v100
	v_rcp_f32_e32 v101, v101
	v_exp_f32_e32 v118, v118
	v_exp_f32_e32 v119, v119
	v_pk_fma_f32 v[120:121], v[100:101], s[10:11], v[104:105] op_sel_hi:[1,0,0]
	s_nop 0
	v_pk_fma_f32 v[120:121], v[100:101], v[120:121], s[14:15] op_sel_hi:[1,1,0]
	s_nop 0
	v_pk_fma_f32 v[120:121], v[100:101], v[120:121], s[36:37] op_sel_hi:[1,1,0]
	s_nop 0
	v_pk_fma_f32 v[120:121], v[100:101], v[120:121], s[66:67] op_sel_hi:[1,1,0]
	s_nop 0
	v_pk_mul_f32 v[100:101], v[100:101], v[120:121]
	v_pk_mul_f32 v[120:121], v[116:117], v[116:117]
	v_pk_mul_f32 v[100:101], v[118:119], v[100:101]
	v_pk_mul_f32 v[120:121], v[120:121], s[4:5] op_sel_hi:[1,0]
	v_pk_mul_f32 v[118:119], v[102:103], v[100:101]
	v_max_f32_e32 v100, 0, v102
	v_max_f32_e32 v101, 0, v103
	v_sub_f32_e64 v100, v100, |v118|
	v_fma_f32 v102, |v116|, s8, 1.0
	v_fma_f32 v103, |v117|, s8, 1.0
	v_sub_f32_e64 v101, v101, |v119|
	v_rcp_f32_e32 v102, v102
	v_rcp_f32_e32 v103, v103
	v_exp_f32_e32 v120, v120
	v_exp_f32_e32 v121, v121
	v_pk_fma_f32 v[118:119], v[102:103], s[10:11], v[104:105] op_sel_hi:[1,0,0]
	s_nop 0
	v_pk_fma_f32 v[118:119], v[102:103], v[118:119], s[14:15] op_sel_hi:[1,1,0]
	s_nop 0
	v_pk_fma_f32 v[118:119], v[102:103], v[118:119], s[36:37] op_sel_hi:[1,1,0]
	s_nop 0
	v_pk_fma_f32 v[118:119], v[102:103], v[118:119], s[66:67] op_sel_hi:[1,1,0]
	s_nop 0
	v_pk_mul_f32 v[102:103], v[102:103], v[118:119]
	v_pk_mul_f32 v[118:119], v[98:99], v[98:99]
	v_pk_mul_f32 v[102:103], v[120:121], v[102:103]
	s_nop 0
	v_pk_mul_f32 v[120:121], v[116:117], v[102:103]
	v_max_f32_e32 v102, 0, v116
	v_max_f32_e32 v103, 0, v117
	v_sub_f32_e64 v102, v102, |v120|
	v_fma_f32 v116, |v98|, s8, 1.0
	v_fma_f32 v117, |v99|, s8, 1.0
	v_sub_f32_e64 v103, v103, |v121|
	v_rcp_f32_e32 v116, v116
	v_rcp_f32_e32 v117, v117
	s_nop 0
	v_pk_fma_f32 v[104:105], v[116:117], s[10:11], v[104:105] op_sel_hi:[1,0,0]
	s_nop 0
	v_pk_fma_f32 v[104:105], v[116:117], v[104:105], s[14:15] op_sel_hi:[1,1,0]
	s_nop 0
	v_pk_fma_f32 v[104:105], v[116:117], v[104:105], s[36:37] op_sel_hi:[1,1,0]
	s_nop 0
	v_pk_fma_f32 v[104:105], v[116:117], v[104:105], s[66:67] op_sel_hi:[1,1,0]
	s_nop 0
	v_pk_mul_f32 v[104:105], v[116:117], v[104:105]
	v_pk_mul_f32 v[116:117], v[118:119], s[4:5] op_sel_hi:[1,0]
	s_nop 0
	v_exp_f32_e32 v116, v116
	v_exp_f32_e32 v117, v117
	s_nop 0
	v_pk_mul_f32 v[104:105], v[116:117], v[104:105]
	s_nop 0
	v_pk_mul_f32 v[116:117], v[98:99], v[104:105]
	v_max_f32_e32 v104, 0, v98
	v_max_f32_e32 v105, 0, v99
	s_nop 0
	v_sub_f32_e64 v98, v104, |v116|
	v_cndmask_b32_e64 v104, 0, 1, s[64:65]
	v_cmp_ne_u32_e64 s[44:45], 1, v104
	v_sub_f32_e64 v99, v105, |v117|
	s_andn2_b64 vcc, exec, s[64:65]
	v_cvt_pk_bf16_f32 v116, v96, v97
	v_cvt_pk_bf16_f32 v117, v100, v101
	v_cvt_pk_bf16_f32 v118, v102, v103
	v_cvt_pk_bf16_f32 v119, v98, v99
	global_store_dwordx4 v[112:113], v[116:119], off offset:256 nt
	s_cbranch_vccnz .LBB0_65
	v_mul_f32_e32 v104, v107, v107
	v_mul_f32_e32 v97, v97, v97
	v_fmac_f32_e32 v104, v106, v106
	v_mul_f32_e32 v105, v109, v109
	v_mul_f32_e32 v106, v111, v111
	v_fmac_f32_e32 v97, v96, v96
	v_mul_f32_e32 v96, v101, v101
	v_fmac_f32_e32 v105, v108, v108
	v_fmac_f32_e32 v106, v110, v110
	v_fmac_f32_e32 v96, v100, v100
	v_add_f32_e32 v105, v105, v106
	v_mul_f32_e32 v106, v115, v115
	v_add_f32_e32 v96, v97, v96
	v_mul_f32_e32 v97, v103, v103
	v_fmac_f32_e32 v106, v114, v114
	v_mul_f32_e32 v99, v99, v99
	v_fmac_f32_e32 v97, v102, v102
	v_add_f32_e32 v105, v106, v105
	v_fmac_f32_e32 v99, v98, v98
	v_add_f32_e32 v96, v97, v96
	v_add_f32_e32 v104, v104, v105
	v_add_f32_e32 v96, v99, v96
	v_add_f32_e32 v96, v104, v96
	ds_bpermute_b32 v97, v147, v96
	s_waitcnt lgkmcnt(0)
	v_add_f32_e32 v96, v96, v97
	ds_bpermute_b32 v97, v165, v96
	s_and_saveexec_b64 s[26:27], s[40:41]
	s_cbranch_execz .LBB0_64
	s_waitcnt lgkmcnt(0)
	v_add_f32_e32 v96, v96, v97
	v_mul_f32_e32 v96, 0x4b800000, v96
	v_trunc_f32_e32 v96, v96
	v_mul_f32_e32 v97, 0x2f800000, v96
	v_floor_f32_e32 v97, v97
	v_fmac_f32_e32 v96, 0xcf800000, v97
	v_cvt_u32_f32_e32 v96, v96
	v_cvt_u32_f32_e32 v97, v97
	v_lshl_add_u64 v[98:99], v[142:143], 3, s[52:53]
	global_atomic_add_x2 v[98:99], v[96:97], off offset:128

; __device__ __forceinline__ unsigned long long f2ss(float v) { return (unsigned long long)(v * 16777216.0f); }
; __device__ __forceinline__ u32x4 pack8(f32x4 v0, f32x4 v1) { u32x4 w; w.x = cvt_pk_bf16(v0[0], v0[1]); w.y = cvt_pk_bf16(v0[2], v0[3]); w.z = cvt_pk_bf16(v1[0], v1[1]); w.w = cvt_pk_bf16(v1[2], v1[3]); return w; }
; __device__ __forceinline__ f32x2 gelu_pk(f32x2 v) {
;     const f32x2 av = __builtin_elementwise_abs(v), d = av * 0.2316418882f + 1.0f;
;     f32x2 t; t.x = __builtin_amdgcn_rcpf(d.x); t.y = __builtin_amdgcn_rcpf(d.y);
;     f32x2 q = t * 0.5307027145f + (-0.7265760135f); q = q * t + 0.7107068705f; q = q * t + (-0.142248368f); q = q * t + 0.127414796f; q = q * t;
;     const f32x2 s = (v * v) * (-0.72134752044f);
;     f32x2 e; e.x = __builtin_amdgcn_exp2f(s.x); e.y = __builtin_amdgcn_exp2f(s.y);
;     const f32x2 m = v * (q * e), r = v - m;
;     f32x2 o; o.x = v.x < 0.f ? m.x : r.x; o.y = v.y < 0.f ? m.y : r.y; return o;
; }
;     __device__ __forceinline__ void operator()(const f32x4 (&acc)[2][2][4][2], const Unit& u, int wr, int wc, int fr, int fq, const Pre& pre) const {
;     ...
;             for (int m = 0; m < 4; ++m) { const int row = row0 + ai * HALF + m * 16; const float r = rs8[ai * 4 + m];
;                 bf16_t* rowp = O + (size_t)row * 2048 + col0; float sq = 0.f;
; #pragma unroll
;                 for (int bj = 0; bj < 2; ++bj) { f32x4 v0 = acc[ai][bj][m][0] * r, v1 = acc[ai][bj][m][1] * r;
;                     f32x2 a = gelu_pk((f32x2){v0[0], v0[1]}), b = gelu_pk((f32x2){v0[2], v0[3]}), c = gelu_pk((f32x2){v1[0], v1[1]}), d = gelu_pk((f32x2){v1[2], v1[3]});
;                     v0 = (f32x4){a.x, a.y, b.x, b.y}; v1 = (f32x4){c.x, c.y, d.x, d.y};
;                     sq += (v0[0] * v0[0] + v0[1] * v0[1]) + (v0[2] * v0[2] + v0[3] * v0[3]) + (v1[0] * v1[0] + v1[1] * v1[1]) + (v1[2] * v1[2] + v1[3] * v1[3]);
;                     *(u32x4*)(rowp + bj * HALF) = pack8(v0, v1); }
;                 if (isv) { sq += __shfl_xor(sq, 16); sq += __shfl_xor(sq, 32); if (fq == 0) atomicAdd(vss + row, f2ss(sq)); } }
.LBB0_65:
	v_pk_mul_f32 v[92:93], v[92:93], v[164:165] op_sel_hi:[1,0]
	v_pk_mul_f32 v[98:99], v[88:89], v[164:165] op_sel_hi:[1,0]
	v_fma_f32 v88, |v92|, s8, 1.0
	v_fma_f32 v89, |v93|, s8, 1.0
	v_pk_mul_f32 v[104:105], v[92:93], v[92:93]
	v_rcp_f32_e32 v100, v88
	v_rcp_f32_e32 v101, v89
	v_mov_b64_e32 v[88:89], s[12:13]
	v_pk_mul_f32 v[104:105], v[104:105], s[4:5] op_sel_hi:[1,0]
	v_pk_fma_f32 v[102:103], v[100:101], s[10:11], v[88:89] op_sel_hi:[1,0,0]
	v_exp_f32_e32 v104, v104
	v_pk_fma_f32 v[102:103], v[100:101], v[102:103], s[14:15] op_sel_hi:[1,1,0]
	v_exp_f32_e32 v105, v105
	v_pk_fma_f32 v[102:103], v[100:101], v[102:103], s[36:37] op_sel_hi:[1,1,0]
	v_pk_mul_f32 v[94:95], v[94:95], v[164:165] op_sel_hi:[1,0]
	v_pk_fma_f32 v[102:103], v[100:101], v[102:103], s[66:67] op_sel_hi:[1,1,0]
	v_pk_mul_f32 v[90:91], v[90:91], v[164:165] op_sel_hi:[1,0]
	v_pk_mul_f32 v[100:101], v[100:101], v[102:103]
	v_pk_mul_f32 v[102:103], v[94:95], v[94:95]
	v_pk_mul_f32 v[100:101], v[104:105], v[100:101]
	v_pk_mul_f32 v[102:103], v[102:103], s[4:5] op_sel_hi:[1,0]
	v_pk_mul_f32 v[104:105], v[92:93], v[100:101]
	v_max_f32_e32 v100, 0, v92
	v_max_f32_e32 v101, 0, v93
	v_exp_f32_e32 v102, v102
	v_sub_f32_e64 v92, v100, |v104|
	v_exp_f32_e32 v103, v103
	v_sub_f32_e64 v93, v101, |v105|
	v_fma_f32 v100, |v94|, s8, 1.0
	v_fma_f32 v101, |v95|, s8, 1.0
	v_rcp_f32_e32 v100, v100
	v_rcp_f32_e32 v101, v101
	v_or_b32_e32 v96, 32, v142
	s_waitcnt lgkmcnt(0)
	v_ashrrev_i32_e32 v97, 31, v96
	v_lshlrev_b64 v[96:97], 12, v[96:97]
	v_pk_fma_f32 v[104:105], v[100:101], s[10:11], v[88:89] op_sel_hi:[1,0,0]
	v_lshl_add_u64 v[96:97], s[30:31], 0, v[96:97]
	v_pk_fma_f32 v[104:105], v[100:101], v[104:105], s[14:15] op_sel_hi:[1,1,0]
	v_lshl_add_u64 v[96:97], v[162:163], 1, v[96:97]
	v_pk_fma_f32 v[104:105], v[100:101], v[104:105], s[36:37] op_sel_hi:[1,1,0]
	v_pk_mul_f32 v[84:85], v[84:85], v[164:165] op_sel_hi:[1,0]
	v_pk_fma_f32 v[104:105], v[100:101], v[104:105], s[66:67] op_sel_hi:[1,1,0]
	v_pk_mul_f32 v[86:87], v[86:87], v[164:165] op_sel_hi:[1,0]
	v_pk_mul_f32 v[100:101], v[100:101], v[104:105]
	v_pk_mul_f32 v[104:105], v[98:99], v[98:99]
	v_pk_mul_f32 v[100:101], v[102:103], v[100:101]
	v_pk_mul_f32 v[104:105], v[104:105], s[4:5] op_sel_hi:[1,0]
	v_pk_mul_f32 v[102:103], v[94:95], v[100:101]
	v_max_f32_e32 v100, 0, v94
	v_max_f32_e32 v101, 0, v95
	v_exp_f32_e32 v104, v104
	v_sub_f32_e64 v94, v100, |v102|
	v_exp_f32_e32 v105, v105
	v_sub_f32_e64 v95, v101, |v103|
	v_fma_f32 v100, |v98|, s8, 1.0
	v_fma_f32 v101, |v99|, s8, 1.0
	v_rcp_f32_e32 v100, v100
	v_rcp_f32_e32 v101, v101
	v_pk_mul_f32 v[82:83], v[82:83], v[164:165] op_sel_hi:[1,0]
	v_pk_fma_f32 v[102:103], v[100:101], s[10:11], v[88:89] op_sel_hi:[1,0,0]
	s_nop 0
	v_pk_fma_f32 v[102:103], v[100:101], v[102:103], s[14:15] op_sel_hi:[1,1,0]
	s_nop 0
	v_pk_fma_f32 v[102:103], v[100:101], v[102:103], s[36:37] op_sel_hi:[1,1,0]
	s_nop 0
	v_pk_fma_f32 v[102:103], v[100:101], v[102:103], s[66:67] op_sel_hi:[1,1,0]
	s_nop 0
	v_pk_mul_f32 v[100:101], v[100:101], v[102:103]
	v_pk_mul_f32 v[102:103], v[90:91], v[90:91]
	v_pk_mul_f32 v[100:101], v[104:105], v[100:101]
	v_pk_mul_f32 v[102:103], v[102:103], s[4:5] op_sel_hi:[1,0]
	v_pk_mul_f32 v[104:105], v[98:99], v[100:101]
	v_max_f32_e32 v100, 0, v98
	v_max_f32_e32 v101, 0, v99
	v_exp_f32_e32 v102, v102
	v_sub_f32_e64 v98, v100, |v104|
	v_exp_f32_e32 v103, v103
	v_sub_f32_e64 v99, v101, |v105|
	v_fma_f32 v100, |v90|, s8, 1.0
	v_fma_f32 v101, |v91|, s8, 1.0
	v_rcp_f32_e32 v100, v100
	v_rcp_f32_e32 v101, v101
	s_nop 0
	v_pk_fma_f32 v[104:105], v[100:101], s[10:11], v[88:89] op_sel_hi:[1,0,0]
	s_nop 0
	v_pk_fma_f32 v[104:105], v[100:101], v[104:105], s[14:15] op_sel_hi:[1,1,0]
	s_nop 0
	v_pk_fma_f32 v[104:105], v[100:101], v[104:105], s[36:37] op_sel_hi:[1,1,0]
	s_nop 0
	v_pk_fma_f32 v[104:105], v[100:101], v[104:105], s[66:67] op_sel_hi:[1,1,0]
	s_nop 0
	v_pk_mul_f32 v[100:101], v[100:101], v[104:105]
	v_pk_mul_f32 v[104:105], v[84:85], v[84:85]
	v_pk_mul_f32 v[100:101], v[102:103], v[100:101]
	v_pk_mul_f32 v[104:105], v[104:105], s[4:5] op_sel_hi:[1,0]
	v_pk_mul_f32 v[102:103], v[90:91], v[100:101]
	v_max_f32_e32 v100, 0, v90
	v_max_f32_e32 v101, 0, v91
	v_exp_f32_e32 v104, v104
	v_sub_f32_e64 v90, v100, |v102|
	v_cvt_pk_bf16_f32 v100, v92, v93
	v_exp_f32_e32 v105, v105
	s_nop 0
	v_sub_f32_e64 v91, v101, |v103|
	v_cvt_pk_bf16_f32 v101, v94, v95
	v_cvt_pk_bf16_f32 v102, v98, v99
	v_cvt_pk_bf16_f32 v103, v90, v91
	global_store_dwordx4 v[96:97], v[100:103], off nt
	s_nop 0
	s_nop 0
	v_pk_mul_f32 v[100:101], v[80:81], v[164:165] op_sel_hi:[1,0]
	v_fma_f32 v80, |v84|, s8, 1.0
	v_fma_f32 v81, |v85|, s8, 1.0
	s_nop 0
	v_rcp_f32_e32 v80, v80
	v_rcp_f32_e32 v81, v81
	s_nop 0
; __device__ __forceinline__ unsigned long long f2ss(float v) { return (unsigned long long)(v * 16777216.0f); }
; __device__ __forceinline__ u32x4 pack8(f32x4 v0, f32x4 v1) { u32x4 w; w.x = cvt_pk_bf16(v0[0], v0[1]); w.y = cvt_pk_bf16(v0[2], v0[3]); w.z = cvt_pk_bf16(v1[0], v1[1]); w.w = cvt_pk_bf16(v1[2], v1[3]); return w; }
; __device__ __forceinline__ f32x2 gelu_pk(f32x2 v) {
;     const f32x2 av = __builtin_elementwise_abs(v), d = av * 0.2316418882f + 1.0f;
;     f32x2 t; t.x = __builtin_amdgcn_rcpf(d.x); t.y = __builtin_amdgcn_rcpf(d.y);
;     f32x2 q = t * 0.5307027145f + (-0.7265760135f); q = q * t + 0.7107068705f; q = q * t + (-0.142248368f); q = q * t + 0.127414796f; q = q * t;
;     const f32x2 s = (v * v) * (-0.72134752044f);
;     f32x2 e; e.x = __builtin_amdgcn_exp2f(s.x); e.y = __builtin_amdgcn_exp2f(s.y);
;     const f32x2 m = v * (q * e), r = v - m;
;     f32x2 o; o.x = v.x < 0.f ? m.x : r.x; o.y = v.y < 0.f ? m.y : r.y; return o;
; }
;     __device__ __forceinline__ void operator()(const f32x4 (&acc)[2][2][4][2], const Unit& u, int wr, int wc, int fr, int fq, const Pre& pre) const {
;     ...
;             for (int m = 0; m < 4; ++m) { const int row = row0 + ai * HALF + m * 16; const float r = rs8[ai * 4 + m];
;                 bf16_t* rowp = O + (size_t)row * 2048 + col0; float sq = 0.f;
; #pragma unroll
;                 for (int bj = 0; bj < 2; ++bj) { f32x4 v0 = acc[ai][bj][m][0] * r, v1 = acc[ai][bj][m][1] * r;
;                     f32x2 a = gelu_pk((f32x2){v0[0], v0[1]}), b = gelu_pk((f32x2){v0[2], v0[3]}), c = gelu_pk((f32x2){v1[0], v1[1]}), d = gelu_pk((f32x2){v1[2], v1[3]});
;                     v0 = (f32x4){a.x, a.y, b.x, b.y}; v1 = (f32x4){c.x, c.y, d.x, d.y};
;                     sq += (v0[0] * v0[0] + v0[1] * v0[1]) + (v0[2] * v0[2] + v0[3] * v0[3]) + (v1[0] * v1[0] + v1[1] * v1[1]) + (v1[2] * v1[2] + v1[3] * v1[3]);
;                     *(u32x4*)(rowp + bj * HALF) = pack8(v0, v1); }
;                 if (isv) { sq += __shfl_xor(sq, 16); sq += __shfl_xor(sq, 32); if (fq == 0) atomicAdd(vss + row, f2ss(sq)); } }
	v_pk_fma_f32 v[102:103], v[80:81], s[10:11], v[88:89] op_sel_hi:[1,0,0]
	s_nop 0
	v_pk_fma_f32 v[102:103], v[80:81], v[102:103], s[14:15] op_sel_hi:[1,1,0]
	s_nop 0
	v_pk_fma_f32 v[102:103], v[80:81], v[102:103], s[36:37] op_sel_hi:[1,1,0]
	s_nop 0
	v_pk_fma_f32 v[102:103], v[80:81], v[102:103], s[66:67] op_sel_hi:[1,1,0]
	s_nop 0
	v_pk_mul_f32 v[80:81], v[80:81], v[102:103]
	v_pk_mul_f32 v[102:103], v[86:87], v[86:87]
	v_pk_mul_f32 v[80:81], v[104:105], v[80:81]
	v_pk_mul_f32 v[102:103], v[102:103], s[4:5] op_sel_hi:[1,0]
	v_pk_mul_f32 v[104:105], v[84:85], v[80:81]
	v_max_f32_e32 v80, 0, v84
	v_max_f32_e32 v81, 0, v85
	v_sub_f32_e64 v80, v80, |v104|
	v_fma_f32 v84, |v86|, s8, 1.0
	v_fma_f32 v85, |v87|, s8, 1.0
	v_sub_f32_e64 v81, v81, |v105|
	v_rcp_f32_e32 v84, v84
	v_rcp_f32_e32 v85, v85
	v_exp_f32_e32 v102, v102
	v_exp_f32_e32 v103, v103
	v_pk_fma_f32 v[104:105], v[84:85], s[10:11], v[88:89] op_sel_hi:[1,0,0]
	s_nop 0
	v_pk_fma_f32 v[104:105], v[84:85], v[104:105], s[14:15] op_sel_hi:[1,1,0]
	s_nop 0
	v_pk_fma_f32 v[104:105], v[84:85], v[104:105], s[36:37] op_sel_hi:[1,1,0]
	s_nop 0
	v_pk_fma_f32 v[104:105], v[84:85], v[104:105], s[66:67] op_sel_hi:[1,1,0]
	s_nop 0
	v_pk_mul_f32 v[84:85], v[84:85], v[104:105]
	v_pk_mul_f32 v[104:105], v[100:101], v[100:101]
	v_pk_mul_f32 v[84:85], v[102:103], v[84:85]
	v_pk_mul_f32 v[104:105], v[104:105], s[4:5] op_sel_hi:[1,0]
	v_pk_mul_f32 v[102:103], v[86:87], v[84:85]
	v_max_f32_e32 v84, 0, v86
	v_max_f32_e32 v85, 0, v87
	v_sub_f32_e64 v84, v84, |v102|
	v_fma_f32 v86, |v100|, s8, 1.0
	v_fma_f32 v87, |v101|, s8, 1.0
	v_sub_f32_e64 v85, v85, |v103|
	v_rcp_f32_e32 v86, v86
	v_rcp_f32_e32 v87, v87
	v_exp_f32_e32 v104, v104
	v_exp_f32_e32 v105, v105
	v_pk_fma_f32 v[102:103], v[86:87], s[10:11], v[88:89] op_sel_hi:[1,0,0]
	s_nop 0
	v_pk_fma_f32 v[102:103], v[86:87], v[102:103], s[14:15] op_sel_hi:[1,1,0]
	s_nop 0
	v_pk_fma_f32 v[102:103], v[86:87], v[102:103], s[36:37] op_sel_hi:[1,1,0]
	s_nop 0
	v_pk_fma_f32 v[102:103], v[86:87], v[102:103], s[66:67] op_sel_hi:[1,1,0]
	s_nop 0
	v_pk_mul_f32 v[86:87], v[86:87], v[102:103]
	v_pk_mul_f32 v[102:103], v[82:83], v[82:83]
	v_pk_mul_f32 v[86:87], v[104:105], v[86:87]
	s_nop 0
	v_pk_mul_f32 v[104:105], v[100:101], v[86:87]
	v_max_f32_e32 v86, 0, v100
	v_max_f32_e32 v87, 0, v101
	v_sub_f32_e64 v86, v86, |v104|
	v_fma_f32 v100, |v82|, s8, 1.0
	v_fma_f32 v101, |v83|, s8, 1.0
	v_sub_f32_e64 v87, v87, |v105|
	v_rcp_f32_e32 v100, v100
	v_rcp_f32_e32 v101, v101
	s_nop 0
	v_pk_fma_f32 v[88:89], v[100:101], s[10:11], v[88:89] op_sel_hi:[1,0,0]
	s_nop 0
	v_pk_fma_f32 v[88:89], v[100:101], v[88:89], s[14:15] op_sel_hi:[1,1,0]
	s_nop 0
	v_pk_fma_f32 v[88:89], v[100:101], v[88:89], s[36:37] op_sel_hi:[1,1,0]
	s_nop 0
	v_pk_fma_f32 v[88:89], v[100:101], v[88:89], s[66:67] op_sel_hi:[1,1,0]
	s_nop 0
	v_pk_mul_f32 v[88:89], v[100:101], v[88:89]
	v_pk_mul_f32 v[100:101], v[102:103], s[4:5] op_sel_hi:[1,0]
	s_nop 0
	v_exp_f32_e32 v100, v100
	v_exp_f32_e32 v101, v101
	s_nop 0
	v_pk_mul_f32 v[88:89], v[100:101], v[88:89]
	s_nop 0
	v_pk_mul_f32 v[100:101], v[82:83], v[88:89]
	v_max_f32_e32 v88, 0, v82
	v_max_f32_e32 v89, 0, v83
	s_nop 0
	v_sub_f32_e64 v82, v88, |v100|
	v_cvt_pk_bf16_f32 v100, v80, v81
	s_nop 1
	v_sub_f32_e64 v83, v89, |v101|
	s_and_b64 vcc, exec, s[44:45]
	v_cvt_pk_bf16_f32 v101, v84, v85
	v_cvt_pk_bf16_f32 v102, v86, v87
	v_cvt_pk_bf16_f32 v103, v82, v83
	global_store_dwordx4 v[96:97], v[100:103], off offset:256 nt
	s_cbranch_vccnz .LBB0_69
	v_mul_f32_e32 v88, v91, v91
	v_mul_f32_e32 v81, v81, v81
	v_fmac_f32_e32 v88, v90, v90
	v_mul_f32_e32 v89, v93, v93
	v_mul_f32_e32 v90, v95, v95
	v_fmac_f32_e32 v81, v80, v80
	v_mul_f32_e32 v80, v85, v85
	v_fmac_f32_e32 v89, v92, v92
	v_fmac_f32_e32 v90, v94, v94
	v_fmac_f32_e32 v80, v84, v84
	v_add_f32_e32 v89, v89, v90
	v_mul_f32_e32 v90, v99, v99
	v_add_f32_e32 v80, v81, v80
	v_mul_f32_e32 v81, v87, v87
	v_fmac_f32_e32 v90, v98, v98
	v_mul_f32_e32 v83, v83, v83
	v_fmac_f32_e32 v81, v86, v86
	v_add_f32_e32 v89, v90, v89
	v_fmac_f32_e32 v83, v82, v82
	v_add_f32_e32 v80, v81, v80
	v_add_f32_e32 v88, v88, v89
	v_add_f32_e32 v80, v83, v80
	v_add_f32_e32 v80, v88, v80
	ds_bpermute_b32 v81, v147, v80
	s_waitcnt lgkmcnt(0)
	v_add_f32_e32 v80, v80, v81
	ds_bpermute_b32 v81, v165, v80
	s_and_saveexec_b64 s[26:27], s[40:41]
	s_cbranch_execz .LBB0_68
	s_waitcnt lgkmcnt(0)
	v_add_f32_e32 v80, v80, v81
	v_mul_f32_e32 v80, 0x4b800000, v80
	v_trunc_f32_e32 v80, v80
	v_mul_f32_e32 v81, 0x2f800000, v80
	v_floor_f32_e32 v81, v81
	v_fmac_f32_e32 v80, 0xcf800000, v81
	v_cvt_u32_f32_e32 v80, v80
	v_cvt_u32_f32_e32 v81, v81
	v_lshl_add_u64 v[82:83], v[142:143], 3, s[52:53]
	global_atomic_add_x2 v[82:83], v[80:81], off offset:256

; __device__ __forceinline__ unsigned long long f2ss(float v) { return (unsigned long long)(v * 16777216.0f); }
; __device__ __forceinline__ u32x4 pack8(f32x4 v0, f32x4 v1) { u32x4 w; w.x = cvt_pk_bf16(v0[0], v0[1]); w.y = cvt_pk_bf16(v0[2], v0[3]); w.z = cvt_pk_bf16(v1[0], v1[1]); w.w = cvt_pk_bf16(v1[2], v1[3]); return w; }
; __device__ __forceinline__ f32x2 gelu_pk(f32x2 v) {
;     const f32x2 av = __builtin_elementwise_abs(v), d = av * 0.2316418882f + 1.0f;
;     f32x2 t; t.x = __builtin_amdgcn_rcpf(d.x); t.y = __builtin_amdgcn_rcpf(d.y);
;     f32x2 q = t * 0.5307027145f + (-0.7265760135f); q = q * t + 0.7107068705f; q = q * t + (-0.142248368f); q = q * t + 0.127414796f; q = q * t;
;     const f32x2 s = (v * v) * (-0.72134752044f);
;     f32x2 e; e.x = __builtin_amdgcn_exp2f(s.x); e.y = __builtin_amdgcn_exp2f(s.y);
;     const f32x2 m = v * (q * e), r = v - m;
;     f32x2 o; o.x = v.x < 0.f ? m.x : r.x; o.y = v.y < 0.f ? m.y : r.y; return o;
; }
;     __device__ __forceinline__ void operator()(const f32x4 (&acc)[2][2][4][2], const Unit& u, int wr, int wc, int fr, int fq, const Pre& pre) const {
;     ...
;             for (int m = 0; m < 4; ++m) { const int row = row0 + ai * HALF + m * 16; const float r = rs8[ai * 4 + m];
;                 bf16_t* rowp = O + (size_t)row * 2048 + col0; float sq = 0.f;
; #pragma unroll
;                 for (int bj = 0; bj < 2; ++bj) { f32x4 v0 = acc[ai][bj][m][0] * r, v1 = acc[ai][bj][m][1] * r;
;                     f32x2 a = gelu_pk((f32x2){v0[0], v0[1]}), b = gelu_pk((f32x2){v0[2], v0[3]}), c = gelu_pk((f32x2){v1[0], v1[1]}), d = gelu_pk((f32x2){v1[2], v1[3]});
;                     v0 = (f32x4){a.x, a.y, b.x, b.y}; v1 = (f32x4){c.x, c.y, d.x, d.y};
;                     sq += (v0[0] * v0[0] + v0[1] * v0[1]) + (v0[2] * v0[2] + v0[3] * v0[3]) + (v1[0] * v1[0] + v1[1] * v1[1]) + (v1[2] * v1[2] + v1[3] * v1[3]);
;                     *(u32x4*)(rowp + bj * HALF) = pack8(v0, v1); }
;                 if (isv) { sq += __shfl_xor(sq, 16); sq += __shfl_xor(sq, 32); if (fq == 0) atomicAdd(vss + row, f2ss(sq)); } }
.LBB0_69:
	v_pk_mul_f32 v[76:77], v[76:77], v[160:161] op_sel_hi:[1,0]
	v_pk_mul_f32 v[82:83], v[72:73], v[160:161] op_sel_hi:[1,0]
	v_fma_f32 v72, |v76|, s8, 1.0
	v_fma_f32 v73, |v77|, s8, 1.0
	v_pk_mul_f32 v[88:89], v[76:77], v[76:77]
	v_rcp_f32_e32 v84, v72
	v_rcp_f32_e32 v85, v73
	v_mov_b64_e32 v[72:73], s[12:13]
	v_pk_mul_f32 v[88:89], v[88:89], s[4:5] op_sel_hi:[1,0]
	v_pk_fma_f32 v[86:87], v[84:85], s[10:11], v[72:73] op_sel_hi:[1,0,0]
	v_exp_f32_e32 v88, v88
	v_pk_fma_f32 v[86:87], v[84:85], v[86:87], s[14:15] op_sel_hi:[1,1,0]
	v_exp_f32_e32 v89, v89
	v_pk_fma_f32 v[86:87], v[84:85], v[86:87], s[36:37] op_sel_hi:[1,1,0]
	v_pk_mul_f32 v[78:79], v[78:79], v[160:161] op_sel_hi:[1,0]
	v_pk_fma_f32 v[86:87], v[84:85], v[86:87], s[66:67] op_sel_hi:[1,1,0]
	v_pk_mul_f32 v[74:75], v[74:75], v[160:161] op_sel_hi:[1,0]
	v_pk_mul_f32 v[84:85], v[84:85], v[86:87]
	v_pk_mul_f32 v[86:87], v[78:79], v[78:79]
	v_pk_mul_f32 v[84:85], v[88:89], v[84:85]
	v_pk_mul_f32 v[86:87], v[86:87], s[4:5] op_sel_hi:[1,0]
	v_pk_mul_f32 v[88:89], v[76:77], v[84:85]
	v_max_f32_e32 v84, 0, v76
	v_max_f32_e32 v85, 0, v77
	v_exp_f32_e32 v86, v86
	v_sub_f32_e64 v76, v84, |v88|
	v_exp_f32_e32 v87, v87
	v_sub_f32_e64 v77, v85, |v89|
	v_fma_f32 v84, |v78|, s8, 1.0
	v_fma_f32 v85, |v79|, s8, 1.0
	v_rcp_f32_e32 v84, v84
	v_rcp_f32_e32 v85, v85
	v_or_b32_e32 v80, 48, v142
	s_waitcnt lgkmcnt(0)
	v_ashrrev_i32_e32 v81, 31, v80
	v_lshlrev_b64 v[80:81], 12, v[80:81]
	v_pk_fma_f32 v[88:89], v[84:85], s[10:11], v[72:73] op_sel_hi:[1,0,0]
	v_lshl_add_u64 v[80:81], s[30:31], 0, v[80:81]
	v_pk_fma_f32 v[88:89], v[84:85], v[88:89], s[14:15] op_sel_hi:[1,1,0]
	v_lshl_add_u64 v[80:81], v[162:163], 1, v[80:81]
	v_pk_fma_f32 v[88:89], v[84:85], v[88:89], s[36:37] op_sel_hi:[1,1,0]
	v_pk_mul_f32 v[68:69], v[68:69], v[160:161] op_sel_hi:[1,0]
	v_pk_fma_f32 v[88:89], v[84:85], v[88:89], s[66:67] op_sel_hi:[1,1,0]
	v_pk_mul_f32 v[70:71], v[70:71], v[160:161] op_sel_hi:[1,0]
	v_pk_mul_f32 v[84:85], v[84:85], v[88:89]
	v_pk_mul_f32 v[88:89], v[82:83], v[82:83]
	v_pk_mul_f32 v[84:85], v[86:87], v[84:85]
	v_pk_mul_f32 v[88:89], v[88:89], s[4:5] op_sel_hi:[1,0]
	v_pk_mul_f32 v[86:87], v[78:79], v[84:85]
	v_max_f32_e32 v84, 0, v78
	v_max_f32_e32 v85, 0, v79
	v_exp_f32_e32 v88, v88
	v_sub_f32_e64 v78, v84, |v86|
	v_exp_f32_e32 v89, v89
	v_sub_f32_e64 v79, v85, |v87|
	v_fma_f32 v84, |v82|, s8, 1.0
	v_fma_f32 v85, |v83|, s8, 1.0
	v_rcp_f32_e32 v84, v84
	v_rcp_f32_e32 v85, v85
	v_pk_mul_f32 v[66:67], v[66:67], v[160:161] op_sel_hi:[1,0]
	v_pk_fma_f32 v[86:87], v[84:85], s[10:11], v[72:73] op_sel_hi:[1,0,0]
	s_nop 0
	v_pk_fma_f32 v[86:87], v[84:85], v[86:87], s[14:15] op_sel_hi:[1,1,0]
	s_nop 0
	v_pk_fma_f32 v[86:87], v[84:85], v[86:87], s[36:37] op_sel_hi:[1,1,0]
	s_nop 0
	v_pk_fma_f32 v[86:87], v[84:85], v[86:87], s[66:67] op_sel_hi:[1,1,0]
	s_nop 0
	v_pk_mul_f32 v[84:85], v[84:85], v[86:87]
	v_pk_mul_f32 v[86:87], v[74:75], v[74:75]
	v_pk_mul_f32 v[84:85], v[88:89], v[84:85]
	v_pk_mul_f32 v[86:87], v[86:87], s[4:5] op_sel_hi:[1,0]
	v_pk_mul_f32 v[88:89], v[82:83], v[84:85]
	v_max_f32_e32 v84, 0, v82
	v_max_f32_e32 v85, 0, v83
	v_exp_f32_e32 v86, v86
	v_sub_f32_e64 v82, v84, |v88|
	v_exp_f32_e32 v87, v87
	v_sub_f32_e64 v83, v85, |v89|
	v_fma_f32 v84, |v74|, s8, 1.0
	v_fma_f32 v85, |v75|, s8, 1.0
	v_rcp_f32_e32 v84, v84
	v_rcp_f32_e32 v85, v85
	s_nop 0
	v_pk_fma_f32 v[88:89], v[84:85], s[10:11], v[72:73] op_sel_hi:[1,0,0]
	s_nop 0
	v_pk_fma_f32 v[88:89], v[84:85], v[88:89], s[14:15] op_sel_hi:[1,1,0]
	s_nop 0
	v_pk_fma_f32 v[88:89], v[84:85], v[88:89], s[36:37] op_sel_hi:[1,1,0]
	s_nop 0
	v_pk_fma_f32 v[88:89], v[84:85], v[88:89], s[66:67] op_sel_hi:[1,1,0]
	s_nop 0
	v_pk_mul_f32 v[84:85], v[84:85], v[88:89]
	v_pk_mul_f32 v[88:89], v[68:69], v[68:69]
	v_pk_mul_f32 v[84:85], v[86:87], v[84:85]
	v_pk_mul_f32 v[88:89], v[88:89], s[4:5] op_sel_hi:[1,0]
	v_pk_mul_f32 v[86:87], v[74:75], v[84:85]
	v_max_f32_e32 v84, 0, v74
	v_max_f32_e32 v85, 0, v75
	v_exp_f32_e32 v88, v88
	v_sub_f32_e64 v74, v84, |v86|
	v_cvt_pk_bf16_f32 v84, v76, v77
	v_exp_f32_e32 v89, v89
	s_nop 0
	v_sub_f32_e64 v75, v85, |v87|
	v_cvt_pk_bf16_f32 v85, v78, v79
	v_cvt_pk_bf16_f32 v86, v82, v83
	v_cvt_pk_bf16_f32 v87, v74, v75
	global_store_dwordx4 v[80:81], v[84:87], off nt
	s_nop 0
	s_nop 0
	v_pk_mul_f32 v[84:85], v[64:65], v[160:161] op_sel_hi:[1,0]
	v_fma_f32 v64, |v68|, s8, 1.0
	v_fma_f32 v65, |v69|, s8, 1.0
	s_nop 0
	v_rcp_f32_e32 v64, v64
	v_rcp_f32_e32 v65, v65
	s_nop 0
	v_pk_fma_f32 v[86:87], v[64:65], s[10:11], v[72:73] op_sel_hi:[1,0,0]
; __device__ __forceinline__ unsigned long long f2ss(float v) { return (unsigned long long)(v * 16777216.0f); }
; __device__ __forceinline__ u32x4 pack8(f32x4 v0, f32x4 v1) { u32x4 w; w.x = cvt_pk_bf16(v0[0], v0[1]); w.y = cvt_pk_bf16(v0[2], v0[3]); w.z = cvt_pk_bf16(v1[0], v1[1]); w.w = cvt_pk_bf16(v1[2], v1[3]); return w; }
; __device__ __forceinline__ f32x2 gelu_pk(f32x2 v) {
;     const f32x2 av = __builtin_elementwise_abs(v), d = av * 0.2316418882f + 1.0f;
;     f32x2 t; t.x = __builtin_amdgcn_rcpf(d.x); t.y = __builtin_amdgcn_rcpf(d.y);
;     f32x2 q = t * 0.5307027145f + (-0.7265760135f); q = q * t + 0.7107068705f; q = q * t + (-0.142248368f); q = q * t + 0.127414796f; q = q * t;
;     const f32x2 s = (v * v) * (-0.72134752044f);
;     f32x2 e; e.x = __builtin_amdgcn_exp2f(s.x); e.y = __builtin_amdgcn_exp2f(s.y);
;     const f32x2 m = v * (q * e), r = v - m;
;     f32x2 o; o.x = v.x < 0.f ? m.x : r.x; o.y = v.y < 0.f ? m.y : r.y; return o;
; }
;     __device__ __forceinline__ void operator()(const f32x4 (&acc)[2][2][4][2], const Unit& u, int wr, int wc, int fr, int fq, const Pre& pre) const {
;     ...
;             for (int m = 0; m < 4; ++m) { const int row = row0 + ai * HALF + m * 16; const float r = rs8[ai * 4 + m];
;                 bf16_t* rowp = O + (size_t)row * 2048 + col0; float sq = 0.f;
; #pragma unroll
;                 for (int bj = 0; bj < 2; ++bj) { f32x4 v0 = acc[ai][bj][m][0] * r, v1 = acc[ai][bj][m][1] * r;
;                     f32x2 a = gelu_pk((f32x2){v0[0], v0[1]}), b = gelu_pk((f32x2){v0[2], v0[3]}), c = gelu_pk((f32x2){v1[0], v1[1]}), d = gelu_pk((f32x2){v1[2], v1[3]});
;                     v0 = (f32x4){a.x, a.y, b.x, b.y}; v1 = (f32x4){c.x, c.y, d.x, d.y};
;                     sq += (v0[0] * v0[0] + v0[1] * v0[1]) + (v0[2] * v0[2] + v0[3] * v0[3]) + (v1[0] * v1[0] + v1[1] * v1[1]) + (v1[2] * v1[2] + v1[3] * v1[3]);
;                     *(u32x4*)(rowp + bj * HALF) = pack8(v0, v1); }
;                 if (isv) { sq += __shfl_xor(sq, 16); sq += __shfl_xor(sq, 32); if (fq == 0) atomicAdd(vss + row, f2ss(sq)); } }
	s_nop 0
	v_pk_fma_f32 v[86:87], v[64:65], v[86:87], s[14:15] op_sel_hi:[1,1,0]
	s_nop 0
	v_pk_fma_f32 v[86:87], v[64:65], v[86:87], s[36:37] op_sel_hi:[1,1,0]
	s_nop 0
	v_pk_fma_f32 v[86:87], v[64:65], v[86:87], s[66:67] op_sel_hi:[1,1,0]
	s_nop 0
	v_pk_mul_f32 v[64:65], v[64:65], v[86:87]
	v_pk_mul_f32 v[86:87], v[70:71], v[70:71]
	v_pk_mul_f32 v[64:65], v[88:89], v[64:65]
	v_pk_mul_f32 v[86:87], v[86:87], s[4:5] op_sel_hi:[1,0]
	v_pk_mul_f32 v[88:89], v[68:69], v[64:65]
	v_max_f32_e32 v64, 0, v68
	v_max_f32_e32 v65, 0, v69
	v_sub_f32_e64 v64, v64, |v88|
	v_fma_f32 v68, |v70|, s8, 1.0
	v_fma_f32 v69, |v71|, s8, 1.0
	v_sub_f32_e64 v65, v65, |v89|
	v_rcp_f32_e32 v68, v68
	v_rcp_f32_e32 v69, v69
	v_exp_f32_e32 v86, v86
	v_exp_f32_e32 v87, v87
	v_pk_fma_f32 v[88:89], v[68:69], s[10:11], v[72:73] op_sel_hi:[1,0,0]
	s_nop 0
	v_pk_fma_f32 v[88:89], v[68:69], v[88:89], s[14:15] op_sel_hi:[1,1,0]
	s_nop 0
	v_pk_fma_f32 v[88:89], v[68:69], v[88:89], s[36:37] op_sel_hi:[1,1,0]
	s_nop 0
	v_pk_fma_f32 v[88:89], v[68:69], v[88:89], s[66:67] op_sel_hi:[1,1,0]
	s_nop 0
	v_pk_mul_f32 v[68:69], v[68:69], v[88:89]
	v_pk_mul_f32 v[88:89], v[84:85], v[84:85]
	v_pk_mul_f32 v[68:69], v[86:87], v[68:69]
	v_pk_mul_f32 v[88:89], v[88:89], s[4:5] op_sel_hi:[1,0]
	v_pk_mul_f32 v[86:87], v[70:71], v[68:69]
	v_max_f32_e32 v68, 0, v70
	v_max_f32_e32 v69, 0, v71
	v_sub_f32_e64 v68, v68, |v86|
	v_fma_f32 v70, |v84|, s8, 1.0
	v_fma_f32 v71, |v85|, s8, 1.0
	v_sub_f32_e64 v69, v69, |v87|
	v_rcp_f32_e32 v70, v70
	v_rcp_f32_e32 v71, v71
	v_exp_f32_e32 v88, v88
	v_exp_f32_e32 v89, v89
	v_pk_fma_f32 v[86:87], v[70:71], s[10:11], v[72:73] op_sel_hi:[1,0,0]
	s_nop 0
	v_pk_fma_f32 v[86:87], v[70:71], v[86:87], s[14:15] op_sel_hi:[1,1,0]
	s_nop 0
	v_pk_fma_f32 v[86:87], v[70:71], v[86:87], s[36:37] op_sel_hi:[1,1,0]
	s_nop 0
	v_pk_fma_f32 v[86:87], v[70:71], v[86:87], s[66:67] op_sel_hi:[1,1,0]
	s_nop 0
	v_pk_mul_f32 v[70:71], v[70:71], v[86:87]
	v_pk_mul_f32 v[86:87], v[66:67], v[66:67]
	v_pk_mul_f32 v[70:71], v[88:89], v[70:71]
	s_nop 0
	v_pk_mul_f32 v[88:89], v[84:85], v[70:71]
	v_max_f32_e32 v70, 0, v84
	v_max_f32_e32 v71, 0, v85
	v_sub_f32_e64 v70, v70, |v88|
	v_fma_f32 v84, |v66|, s8, 1.0
	v_fma_f32 v85, |v67|, s8, 1.0
	v_sub_f32_e64 v71, v71, |v89|
	v_rcp_f32_e32 v84, v84
	v_rcp_f32_e32 v85, v85
	s_nop 0
	v_pk_fma_f32 v[72:73], v[84:85], s[10:11], v[72:73] op_sel_hi:[1,0,0]
	s_nop 0
	v_pk_fma_f32 v[72:73], v[84:85], v[72:73], s[14:15] op_sel_hi:[1,1,0]
	s_nop 0
	v_pk_fma_f32 v[72:73], v[84:85], v[72:73], s[36:37] op_sel_hi:[1,1,0]
	s_nop 0
	v_pk_fma_f32 v[72:73], v[84:85], v[72:73], s[66:67] op_sel_hi:[1,1,0]
	s_nop 0
	v_pk_mul_f32 v[72:73], v[84:85], v[72:73]
	v_pk_mul_f32 v[84:85], v[86:87], s[4:5] op_sel_hi:[1,0]
	s_nop 0
	v_exp_f32_e32 v84, v84
	v_exp_f32_e32 v85, v85
	s_nop 0
	v_pk_mul_f32 v[72:73], v[84:85], v[72:73]
	s_nop 0
	v_pk_mul_f32 v[84:85], v[66:67], v[72:73]
	v_max_f32_e32 v72, 0, v66
	v_max_f32_e32 v73, 0, v67
	s_nop 0
	v_sub_f32_e64 v66, v72, |v84|
	v_cvt_pk_bf16_f32 v84, v64, v65
	s_nop 1
	v_sub_f32_e64 v67, v73, |v85|
	s_and_b64 vcc, exec, s[44:45]
	v_cvt_pk_bf16_f32 v85, v68, v69
	v_cvt_pk_bf16_f32 v86, v70, v71
	v_cvt_pk_bf16_f32 v87, v66, v67
	global_store_dwordx4 v[80:81], v[84:87], off offset:256 nt
	s_cbranch_vccnz .LBB0_73
	v_mul_f32_e32 v72, v75, v75
	v_mul_f32_e32 v65, v65, v65
	v_fmac_f32_e32 v72, v74, v74
	v_mul_f32_e32 v73, v77, v77
	v_mul_f32_e32 v74, v79, v79
	v_fmac_f32_e32 v65, v64, v64
	v_mul_f32_e32 v64, v69, v69
	v_fmac_f32_e32 v73, v76, v76
	v_fmac_f32_e32 v74, v78, v78
	v_fmac_f32_e32 v64, v68, v68
	v_add_f32_e32 v73, v73, v74
	v_mul_f32_e32 v74, v83, v83
	v_add_f32_e32 v64, v65, v64
	v_mul_f32_e32 v65, v71, v71
	v_fmac_f32_e32 v74, v82, v82
	v_mul_f32_e32 v67, v67, v67
	v_fmac_f32_e32 v65, v70, v70
	v_add_f32_e32 v73, v74, v73
	v_fmac_f32_e32 v67, v66, v66
	v_add_f32_e32 v64, v65, v64
	v_add_f32_e32 v72, v72, v73
	v_add_f32_e32 v64, v67, v64
	v_add_f32_e32 v64, v72, v64
	ds_bpermute_b32 v65, v147, v64
	s_waitcnt lgkmcnt(0)
	v_add_f32_e32 v64, v64, v65
	ds_bpermute_b32 v65, v165, v64
	s_and_saveexec_b64 s[26:27], s[40:41]
	s_cbranch_execz .LBB0_72
	s_waitcnt lgkmcnt(0)
	v_add_f32_e32 v64, v64, v65
	v_mul_f32_e32 v64, 0x4b800000, v64
	v_trunc_f32_e32 v64, v64
	v_mul_f32_e32 v65, 0x2f800000, v64
	v_floor_f32_e32 v65, v65
	v_fmac_f32_e32 v64, 0xcf800000, v65
	v_cvt_u32_f32_e32 v64, v64
	v_cvt_u32_f32_e32 v65, v65
	v_lshl_add_u64 v[66:67], v[142:143], 3, s[52:53]
	global_atomic_add_x2 v[66:67], v[64:65], off offset:384

; __device__ __forceinline__ unsigned long long f2ss(float v) { return (unsigned long long)(v * 16777216.0f); }
; __device__ __forceinline__ u32x4 pack8(f32x4 v0, f32x4 v1) { u32x4 w; w.x = cvt_pk_bf16(v0[0], v0[1]); w.y = cvt_pk_bf16(v0[2], v0[3]); w.z = cvt_pk_bf16(v1[0], v1[1]); w.w = cvt_pk_bf16(v1[2], v1[3]); return w; }
; __device__ __forceinline__ f32x2 gelu_pk(f32x2 v) {
;     const f32x2 av = __builtin_elementwise_abs(v), d = av * 0.2316418882f + 1.0f;
;     f32x2 t; t.x = __builtin_amdgcn_rcpf(d.x); t.y = __builtin_amdgcn_rcpf(d.y);
;     f32x2 q = t * 0.5307027145f + (-0.7265760135f); q = q * t + 0.7107068705f; q = q * t + (-0.142248368f); q = q * t + 0.127414796f; q = q * t;
;     const f32x2 s = (v * v) * (-0.72134752044f);
;     f32x2 e; e.x = __builtin_amdgcn_exp2f(s.x); e.y = __builtin_amdgcn_exp2f(s.y);
;     const f32x2 m = v * (q * e), r = v - m;
;     f32x2 o; o.x = v.x < 0.f ? m.x : r.x; o.y = v.y < 0.f ? m.y : r.y; return o;
; }
;     __device__ __forceinline__ void operator()(const f32x4 (&acc)[2][2][4][2], const Unit& u, int wr, int wc, int fr, int fq, const Pre& pre) const {
;     ...
;             for (int m = 0; m < 4; ++m) { const int row = row0 + ai * HALF + m * 16; const float r = rs8[ai * 4 + m];
;                 bf16_t* rowp = O + (size_t)row * 2048 + col0; float sq = 0.f;
; #pragma unroll
;                 for (int bj = 0; bj < 2; ++bj) { f32x4 v0 = acc[ai][bj][m][0] * r, v1 = acc[ai][bj][m][1] * r;
;                     f32x2 a = gelu_pk((f32x2){v0[0], v0[1]}), b = gelu_pk((f32x2){v0[2], v0[3]}), c = gelu_pk((f32x2){v1[0], v1[1]}), d = gelu_pk((f32x2){v1[2], v1[3]});
;                     v0 = (f32x4){a.x, a.y, b.x, b.y}; v1 = (f32x4){c.x, c.y, d.x, d.y};
;                     sq += (v0[0] * v0[0] + v0[1] * v0[1]) + (v0[2] * v0[2] + v0[3] * v0[3]) + (v1[0] * v1[0] + v1[1] * v1[1]) + (v1[2] * v1[2] + v1[3] * v1[3]);
;                     *(u32x4*)(rowp + bj * HALF) = pack8(v0, v1); }
;                 if (isv) { sq += __shfl_xor(sq, 16); sq += __shfl_xor(sq, 32); if (fq == 0) atomicAdd(vss + row, f2ss(sq)); } }
.LBB0_73:
	v_pk_mul_f32 v[60:61], v[60:61], v[158:159] op_sel_hi:[1,0]
	v_pk_mul_f32 v[66:67], v[56:57], v[158:159] op_sel_hi:[1,0]
	v_fma_f32 v56, |v60|, s8, 1.0
	v_fma_f32 v57, |v61|, s8, 1.0
	s_mov_b64 s[20:21], 0x80000
	v_rcp_f32_e32 v68, v56
	v_rcp_f32_e32 v69, v57
	s_waitcnt lgkmcnt(0)
	v_lshl_add_u64 v[64:65], v[152:153], 0, s[20:21]
	v_mov_b64_e32 v[56:57], s[12:13]
	v_pk_mul_f32 v[72:73], v[60:61], v[60:61]
	s_mov_b32 s20, 0xbf38aa3b
	v_pk_fma_f32 v[70:71], v[68:69], s[10:11], v[56:57] op_sel_hi:[1,0,0]
	v_pk_mul_f32 v[72:73], v[72:73], s[20:21] op_sel_hi:[1,0]
	v_pk_fma_f32 v[70:71], v[68:69], v[70:71], s[14:15] op_sel_hi:[1,1,0]
	v_exp_f32_e32 v72, v72
	v_exp_f32_e32 v73, v73
	v_pk_fma_f32 v[70:71], v[68:69], v[70:71], s[36:37] op_sel_hi:[1,1,0]
	s_nop 0
	v_pk_fma_f32 v[70:71], v[68:69], v[70:71], s[66:67] op_sel_hi:[1,1,0]
	v_pk_mul_f32 v[62:63], v[62:63], v[158:159] op_sel_hi:[1,0]
	v_pk_mul_f32 v[68:69], v[68:69], v[70:71]
	v_pk_mul_f32 v[70:71], v[62:63], v[62:63]
	v_pk_mul_f32 v[68:69], v[72:73], v[68:69]
	v_pk_mul_f32 v[70:71], v[70:71], s[20:21] op_sel_hi:[1,0]
	v_pk_mul_f32 v[72:73], v[60:61], v[68:69]
	v_max_f32_e32 v68, 0, v60
	v_max_f32_e32 v69, 0, v61
	v_exp_f32_e32 v70, v70
	v_sub_f32_e64 v60, v68, |v72|
	v_exp_f32_e32 v71, v71
	v_sub_f32_e64 v61, v69, |v73|
	v_fma_f32 v68, |v62|, s8, 1.0
	v_fma_f32 v69, |v63|, s8, 1.0
	v_rcp_f32_e32 v68, v68
	v_rcp_f32_e32 v69, v69
	v_pk_mul_f32 v[58:59], v[58:59], v[158:159] op_sel_hi:[1,0]
	s_mov_b32 s4, 0x80000
	v_pk_mul_f32 v[52:53], v[52:53], v[158:159] op_sel_hi:[1,0]
	v_pk_fma_f32 v[72:73], v[68:69], s[10:11], v[56:57] op_sel_hi:[1,0,0]
	v_pk_mul_f32 v[54:55], v[54:55], v[158:159] op_sel_hi:[1,0]
	v_pk_fma_f32 v[72:73], v[68:69], v[72:73], s[14:15] op_sel_hi:[1,1,0]
	v_pk_mul_f32 v[50:51], v[50:51], v[158:159] op_sel_hi:[1,0]
	v_pk_fma_f32 v[72:73], v[68:69], v[72:73], s[36:37] op_sel_hi:[1,1,0]
	s_nop 0
	v_pk_fma_f32 v[72:73], v[68:69], v[72:73], s[66:67] op_sel_hi:[1,1,0]
	s_nop 0
	v_pk_mul_f32 v[68:69], v[68:69], v[72:73]
	v_pk_mul_f32 v[72:73], v[66:67], v[66:67]
	v_pk_mul_f32 v[68:69], v[70:71], v[68:69]
	v_pk_mul_f32 v[72:73], v[72:73], s[20:21] op_sel_hi:[1,0]
	v_pk_mul_f32 v[70:71], v[62:63], v[68:69]
	v_max_f32_e32 v68, 0, v62
	v_max_f32_e32 v69, 0, v63
	v_exp_f32_e32 v72, v72
	v_sub_f32_e64 v62, v68, |v70|
	v_exp_f32_e32 v73, v73
	v_sub_f32_e64 v63, v69, |v71|
	v_fma_f32 v68, |v66|, s8, 1.0
	v_fma_f32 v69, |v67|, s8, 1.0
	v_rcp_f32_e32 v68, v68
	v_rcp_f32_e32 v69, v69
	s_nop 0
	v_pk_fma_f32 v[70:71], v[68:69], s[10:11], v[56:57] op_sel_hi:[1,0,0]
	s_nop 0
	v_pk_fma_f32 v[70:71], v[68:69], v[70:71], s[14:15] op_sel_hi:[1,1,0]
	s_nop 0
	v_pk_fma_f32 v[70:71], v[68:69], v[70:71], s[36:37] op_sel_hi:[1,1,0]
	s_nop 0
	v_pk_fma_f32 v[70:71], v[68:69], v[70:71], s[66:67] op_sel_hi:[1,1,0]
	s_nop 0
	v_pk_mul_f32 v[68:69], v[68:69], v[70:71]
	v_pk_mul_f32 v[70:71], v[58:59], v[58:59]
	v_pk_mul_f32 v[68:69], v[72:73], v[68:69]
	v_pk_mul_f32 v[70:71], v[70:71], s[20:21] op_sel_hi:[1,0]
	v_pk_mul_f32 v[72:73], v[66:67], v[68:69]
	v_max_f32_e32 v68, 0, v66
	v_max_f32_e32 v69, 0, v67
	v_exp_f32_e32 v70, v70
	v_sub_f32_e64 v66, v68, |v72|
	v_exp_f32_e32 v71, v71
	v_sub_f32_e64 v67, v69, |v73|
	v_fma_f32 v68, |v58|, s8, 1.0
	v_fma_f32 v69, |v59|, s8, 1.0
	v_rcp_f32_e32 v68, v68
	v_rcp_f32_e32 v69, v69
	s_nop 0
	v_pk_fma_f32 v[72:73], v[68:69], s[10:11], v[56:57] op_sel_hi:[1,0,0]
	s_nop 0
	v_pk_fma_f32 v[72:73], v[68:69], v[72:73], s[14:15] op_sel_hi:[1,1,0]
	s_nop 0
	v_pk_fma_f32 v[72:73], v[68:69], v[72:73], s[36:37] op_sel_hi:[1,1,0]
	s_nop 0
	v_pk_fma_f32 v[72:73], v[68:69], v[72:73], s[66:67] op_sel_hi:[1,1,0]
	s_nop 0
	v_pk_mul_f32 v[68:69], v[68:69], v[72:73]
	s_nop 0
	v_pk_mul_f32 v[68:69], v[70:71], v[68:69]
	s_nop 0
	v_pk_mul_f32 v[70:71], v[58:59], v[68:69]
	v_max_f32_e32 v68, 0, v58
	v_max_f32_e32 v69, 0, v59
	s_nop 0
	v_sub_f32_e64 v58, v68, |v70|
	v_cvt_pk_bf16_f32 v68, v60, v61
	s_nop 1
	v_sub_f32_e64 v59, v69, |v71|
	v_add_co_u32_e32 v72, vcc, s4, v152
	v_cvt_pk_bf16_f32 v69, v62, v63
	v_cvt_pk_bf16_f32 v70, v66, v67
	v_cvt_pk_bf16_f32 v71, v58, v59
	s_nop 1
	v_addc_co_u32_e32 v73, vcc, 0, v153, vcc
	global_store_dwordx4 v[72:73], v[68:71], off nt
	v_pk_mul_f32 v[72:73], v[52:53], v[52:53]
	s_nop 0
	v_pk_mul_f32 v[68:69], v[48:49], v[158:159] op_sel_hi:[1,0]
	v_fma_f32 v48, |v52|, s8, 1.0
	v_fma_f32 v49, |v53|, s8, 1.0
	v_pk_mul_f32 v[72:73], v[72:73], s[20:21] op_sel_hi:[1,0]
	v_rcp_f32_e32 v48, v48
	v_rcp_f32_e32 v49, v49
	v_exp_f32_e32 v72, v72
	v_exp_f32_e32 v73, v73
; __device__ __forceinline__ unsigned long long f2ss(float v) { return (unsigned long long)(v * 16777216.0f); }
; __device__ __forceinline__ u32x4 pack8(f32x4 v0, f32x4 v1) { u32x4 w; w.x = cvt_pk_bf16(v0[0], v0[1]); w.y = cvt_pk_bf16(v0[2], v0[3]); w.z = cvt_pk_bf16(v1[0], v1[1]); w.w = cvt_pk_bf16(v1[2], v1[3]); return w; }
; __device__ __forceinline__ f32x2 gelu_pk(f32x2 v) {
;     const f32x2 av = __builtin_elementwise_abs(v), d = av * 0.2316418882f + 1.0f;
;     f32x2 t; t.x = __builtin_amdgcn_rcpf(d.x); t.y = __builtin_amdgcn_rcpf(d.y);
;     f32x2 q = t * 0.5307027145f + (-0.7265760135f); q = q * t + 0.7107068705f; q = q * t + (-0.142248368f); q = q * t + 0.127414796f; q = q * t;
;     const f32x2 s = (v * v) * (-0.72134752044f);
;     f32x2 e; e.x = __builtin_amdgcn_exp2f(s.x); e.y = __builtin_amdgcn_exp2f(s.y);
;     const f32x2 m = v * (q * e), r = v - m;
;     f32x2 o; o.x = v.x < 0.f ? m.x : r.x; o.y = v.y < 0.f ? m.y : r.y; return o;
; }
;     __device__ __forceinline__ void operator()(const f32x4 (&acc)[2][2][4][2], const Unit& u, int wr, int wc, int fr, int fq, const Pre& pre) const {
;     ...
;             for (int m = 0; m < 4; ++m) { const int row = row0 + ai * HALF + m * 16; const float r = rs8[ai * 4 + m];
;                 bf16_t* rowp = O + (size_t)row * 2048 + col0; float sq = 0.f;
; #pragma unroll
;                 for (int bj = 0; bj < 2; ++bj) { f32x4 v0 = acc[ai][bj][m][0] * r, v1 = acc[ai][bj][m][1] * r;
;                     f32x2 a = gelu_pk((f32x2){v0[0], v0[1]}), b = gelu_pk((f32x2){v0[2], v0[3]}), c = gelu_pk((f32x2){v1[0], v1[1]}), d = gelu_pk((f32x2){v1[2], v1[3]});
;                     v0 = (f32x4){a.x, a.y, b.x, b.y}; v1 = (f32x4){c.x, c.y, d.x, d.y};
;                     sq += (v0[0] * v0[0] + v0[1] * v0[1]) + (v0[2] * v0[2] + v0[3] * v0[3]) + (v1[0] * v1[0] + v1[1] * v1[1]) + (v1[2] * v1[2] + v1[3] * v1[3]);
;                     *(u32x4*)(rowp + bj * HALF) = pack8(v0, v1); }
;                 if (isv) { sq += __shfl_xor(sq, 16); sq += __shfl_xor(sq, 32); if (fq == 0) atomicAdd(vss + row, f2ss(sq)); } }
	v_pk_fma_f32 v[70:71], v[48:49], s[10:11], v[56:57] op_sel_hi:[1,0,0]
	s_nop 0
	v_pk_fma_f32 v[70:71], v[48:49], v[70:71], s[14:15] op_sel_hi:[1,1,0]
	s_nop 0
	v_pk_fma_f32 v[70:71], v[48:49], v[70:71], s[36:37] op_sel_hi:[1,1,0]
	s_nop 0
	v_pk_fma_f32 v[70:71], v[48:49], v[70:71], s[66:67] op_sel_hi:[1,1,0]
	s_nop 0
	v_pk_mul_f32 v[48:49], v[48:49], v[70:71]
	v_pk_mul_f32 v[70:71], v[54:55], v[54:55]
	v_pk_mul_f32 v[48:49], v[72:73], v[48:49]
	v_pk_mul_f32 v[70:71], v[70:71], s[20:21] op_sel_hi:[1,0]
	v_pk_mul_f32 v[72:73], v[52:53], v[48:49]
	v_max_f32_e32 v48, 0, v52
	v_max_f32_e32 v49, 0, v53
	v_sub_f32_e64 v48, v48, |v72|
	v_fma_f32 v52, |v54|, s8, 1.0
	v_fma_f32 v53, |v55|, s8, 1.0
	v_sub_f32_e64 v49, v49, |v73|
	v_rcp_f32_e32 v52, v52
	v_rcp_f32_e32 v53, v53
	v_exp_f32_e32 v70, v70
	v_exp_f32_e32 v71, v71
	v_pk_fma_f32 v[72:73], v[52:53], s[10:11], v[56:57] op_sel_hi:[1,0,0]
	s_nop 0
	v_pk_fma_f32 v[72:73], v[52:53], v[72:73], s[14:15] op_sel_hi:[1,1,0]
	s_nop 0
	v_pk_fma_f32 v[72:73], v[52:53], v[72:73], s[36:37] op_sel_hi:[1,1,0]
	s_nop 0
	v_pk_fma_f32 v[72:73], v[52:53], v[72:73], s[66:67] op_sel_hi:[1,1,0]
	s_nop 0
	v_pk_mul_f32 v[52:53], v[52:53], v[72:73]
	v_pk_mul_f32 v[72:73], v[68:69], v[68:69]
	v_pk_mul_f32 v[52:53], v[70:71], v[52:53]
	v_pk_mul_f32 v[72:73], v[72:73], s[20:21] op_sel_hi:[1,0]
	v_pk_mul_f32 v[70:71], v[54:55], v[52:53]
	v_max_f32_e32 v52, 0, v54
	v_max_f32_e32 v53, 0, v55
	v_sub_f32_e64 v52, v52, |v70|
	v_fma_f32 v54, |v68|, s8, 1.0
	v_fma_f32 v55, |v69|, s8, 1.0
	v_sub_f32_e64 v53, v53, |v71|
	v_rcp_f32_e32 v54, v54
	v_rcp_f32_e32 v55, v55
	v_exp_f32_e32 v72, v72
	v_exp_f32_e32 v73, v73
	v_pk_fma_f32 v[70:71], v[54:55], s[10:11], v[56:57] op_sel_hi:[1,0,0]
	s_nop 0
	v_pk_fma_f32 v[70:71], v[54:55], v[70:71], s[14:15] op_sel_hi:[1,1,0]
	s_nop 0
	v_pk_fma_f32 v[70:71], v[54:55], v[70:71], s[36:37] op_sel_hi:[1,1,0]
	s_nop 0
	v_pk_fma_f32 v[70:71], v[54:55], v[70:71], s[66:67] op_sel_hi:[1,1,0]
	s_nop 0
	v_pk_mul_f32 v[54:55], v[54:55], v[70:71]
	v_pk_mul_f32 v[70:71], v[50:51], v[50:51]
	v_pk_mul_f32 v[54:55], v[72:73], v[54:55]
	s_nop 0
	v_pk_mul_f32 v[72:73], v[68:69], v[54:55]
	v_max_f32_e32 v54, 0, v68
	v_max_f32_e32 v55, 0, v69
	v_sub_f32_e64 v54, v54, |v72|
	v_fma_f32 v68, |v50|, s8, 1.0
	v_fma_f32 v69, |v51|, s8, 1.0
	v_sub_f32_e64 v55, v55, |v73|
	v_rcp_f32_e32 v68, v68
	v_rcp_f32_e32 v69, v69
	s_nop 0
	v_pk_fma_f32 v[56:57], v[68:69], s[10:11], v[56:57] op_sel_hi:[1,0,0]
	s_nop 0
	v_pk_fma_f32 v[56:57], v[68:69], v[56:57], s[14:15] op_sel_hi:[1,1,0]
	s_nop 0
	v_pk_fma_f32 v[56:57], v[68:69], v[56:57], s[36:37] op_sel_hi:[1,1,0]
	s_nop 0
	v_pk_fma_f32 v[56:57], v[68:69], v[56:57], s[66:67] op_sel_hi:[1,1,0]
	s_nop 0
	v_pk_mul_f32 v[56:57], v[68:69], v[56:57]
	v_pk_mul_f32 v[68:69], v[70:71], s[20:21] op_sel_hi:[1,0]
	s_nop 0
	v_exp_f32_e32 v68, v68
	v_exp_f32_e32 v69, v69
	s_nop 0
	v_pk_mul_f32 v[56:57], v[68:69], v[56:57]
	s_nop 0
	v_pk_mul_f32 v[68:69], v[50:51], v[56:57]
	v_max_f32_e32 v56, 0, v50
	v_max_f32_e32 v57, 0, v51
	s_nop 0
	v_sub_f32_e64 v50, v56, |v68|
	v_cvt_pk_bf16_f32 v68, v48, v49
	s_nop 1
	v_sub_f32_e64 v51, v57, |v69|
	s_and_b64 vcc, exec, s[44:45]
	v_cvt_pk_bf16_f32 v69, v52, v53
	v_cvt_pk_bf16_f32 v70, v54, v55
	v_cvt_pk_bf16_f32 v71, v50, v51
	global_store_dwordx4 v[64:65], v[68:71], off offset:256 nt
	s_cbranch_vccnz .LBB0_77
	v_mul_f32_e32 v56, v59, v59
	v_mul_f32_e32 v49, v49, v49
	v_fmac_f32_e32 v56, v58, v58
	v_mul_f32_e32 v57, v61, v61
	v_mul_f32_e32 v58, v63, v63
	v_fmac_f32_e32 v49, v48, v48
	v_mul_f32_e32 v48, v53, v53
	v_fmac_f32_e32 v57, v60, v60
	v_fmac_f32_e32 v58, v62, v62
	v_fmac_f32_e32 v48, v52, v52
	v_add_f32_e32 v57, v57, v58
	v_mul_f32_e32 v58, v67, v67
	v_add_f32_e32 v48, v49, v48
	v_mul_f32_e32 v49, v55, v55
	v_fmac_f32_e32 v58, v66, v66
	v_mul_f32_e32 v51, v51, v51
	v_fmac_f32_e32 v49, v54, v54
	v_add_f32_e32 v57, v58, v57
	v_fmac_f32_e32 v51, v50, v50
	v_add_f32_e32 v48, v49, v48
	v_add_f32_e32 v56, v56, v57
	v_add_f32_e32 v48, v51, v48
	v_add_f32_e32 v48, v56, v48
	ds_bpermute_b32 v49, v147, v48
	s_waitcnt lgkmcnt(0)
	v_add_f32_e32 v48, v48, v49
	ds_bpermute_b32 v49, v165, v48
	s_and_saveexec_b64 s[26:27], s[40:41]
	s_cbranch_execz .LBB0_76
	s_waitcnt lgkmcnt(0)
	v_add_f32_e32 v48, v48, v49
	v_mul_f32_e32 v48, 0x4b800000, v48
	v_trunc_f32_e32 v48, v48
	v_mul_f32_e32 v49, 0x2f800000, v48
	v_floor_f32_e32 v49, v49
	v_fmac_f32_e32 v48, 0xcf800000, v49
	v_cvt_u32_f32_e32 v48, v48
	v_cvt_u32_f32_e32 v49, v49
	v_lshl_add_u64 v[50:51], v[142:143], 3, s[52:53]
	global_atomic_add_x2 v[50:51], v[48:49], off offset:1024

; __device__ __forceinline__ unsigned long long f2ss(float v) { return (unsigned long long)(v * 16777216.0f); }
; __device__ __forceinline__ u32x4 pack8(f32x4 v0, f32x4 v1) { u32x4 w; w.x = cvt_pk_bf16(v0[0], v0[1]); w.y = cvt_pk_bf16(v0[2], v0[3]); w.z = cvt_pk_bf16(v1[0], v1[1]); w.w = cvt_pk_bf16(v1[2], v1[3]); return w; }
; __device__ __forceinline__ f32x2 gelu_pk(f32x2 v) {
;     const f32x2 av = __builtin_elementwise_abs(v), d = av * 0.2316418882f + 1.0f;
;     f32x2 t; t.x = __builtin_amdgcn_rcpf(d.x); t.y = __builtin_amdgcn_rcpf(d.y);
;     f32x2 q = t * 0.5307027145f + (-0.7265760135f); q = q * t + 0.7107068705f; q = q * t + (-0.142248368f); q = q * t + 0.127414796f; q = q * t;
;     const f32x2 s = (v * v) * (-0.72134752044f);
;     f32x2 e; e.x = __builtin_amdgcn_exp2f(s.x); e.y = __builtin_amdgcn_exp2f(s.y);
;     const f32x2 m = v * (q * e), r = v - m;
;     f32x2 o; o.x = v.x < 0.f ? m.x : r.x; o.y = v.y < 0.f ? m.y : r.y; return o;
; }
;     __device__ __forceinline__ void operator()(const f32x4 (&acc)[2][2][4][2], const Unit& u, int wr, int wc, int fr, int fq, const Pre& pre) const {
;     ...
;             for (int m = 0; m < 4; ++m) { const int row = row0 + ai * HALF + m * 16; const float r = rs8[ai * 4 + m];
;                 bf16_t* rowp = O + (size_t)row * 2048 + col0; float sq = 0.f;
; #pragma unroll
;                 for (int bj = 0; bj < 2; ++bj) { f32x4 v0 = acc[ai][bj][m][0] * r, v1 = acc[ai][bj][m][1] * r;
;                     f32x2 a = gelu_pk((f32x2){v0[0], v0[1]}), b = gelu_pk((f32x2){v0[2], v0[3]}), c = gelu_pk((f32x2){v1[0], v1[1]}), d = gelu_pk((f32x2){v1[2], v1[3]});
;                     v0 = (f32x4){a.x, a.y, b.x, b.y}; v1 = (f32x4){c.x, c.y, d.x, d.y};
;                     sq += (v0[0] * v0[0] + v0[1] * v0[1]) + (v0[2] * v0[2] + v0[3] * v0[3]) + (v1[0] * v1[0] + v1[1] * v1[1]) + (v1[2] * v1[2] + v1[3] * v1[3]);
;                     *(u32x4*)(rowp + bj * HALF) = pack8(v0, v1); }
;                 if (isv) { sq += __shfl_xor(sq, 16); sq += __shfl_xor(sq, 32); if (fq == 0) atomicAdd(vss + row, f2ss(sq)); } }
.LBB0_77:
	v_pk_mul_f32 v[44:45], v[44:45], v[156:157] op_sel_hi:[1,0]
	v_pk_mul_f32 v[50:51], v[40:41], v[156:157] op_sel_hi:[1,0]
	v_fma_f32 v40, |v44|, s8, 1.0
	v_fma_f32 v41, |v45|, s8, 1.0
	s_mov_b64 s[20:21], 0x90000
	v_rcp_f32_e32 v52, v40
	v_rcp_f32_e32 v53, v41
	s_waitcnt lgkmcnt(0)
	v_lshl_add_u64 v[48:49], v[152:153], 0, s[20:21]
	v_mov_b64_e32 v[40:41], s[12:13]
	v_pk_mul_f32 v[56:57], v[44:45], v[44:45]
	s_mov_b32 s20, 0xbf38aa3b
	v_pk_fma_f32 v[54:55], v[52:53], s[10:11], v[40:41] op_sel_hi:[1,0,0]
	v_pk_mul_f32 v[56:57], v[56:57], s[20:21] op_sel_hi:[1,0]
	v_pk_fma_f32 v[54:55], v[52:53], v[54:55], s[14:15] op_sel_hi:[1,1,0]
	v_exp_f32_e32 v56, v56
	v_exp_f32_e32 v57, v57
	v_pk_fma_f32 v[54:55], v[52:53], v[54:55], s[36:37] op_sel_hi:[1,1,0]
	s_nop 0
	v_pk_fma_f32 v[54:55], v[52:53], v[54:55], s[66:67] op_sel_hi:[1,1,0]
	v_pk_mul_f32 v[46:47], v[46:47], v[156:157] op_sel_hi:[1,0]
	v_pk_mul_f32 v[52:53], v[52:53], v[54:55]
	v_pk_mul_f32 v[54:55], v[46:47], v[46:47]
	v_pk_mul_f32 v[52:53], v[56:57], v[52:53]
	v_pk_mul_f32 v[54:55], v[54:55], s[20:21] op_sel_hi:[1,0]
	v_pk_mul_f32 v[56:57], v[44:45], v[52:53]
	v_max_f32_e32 v52, 0, v44
	v_max_f32_e32 v53, 0, v45
	v_exp_f32_e32 v54, v54
	v_sub_f32_e64 v44, v52, |v56|
	v_exp_f32_e32 v55, v55
	v_sub_f32_e64 v45, v53, |v57|
	v_fma_f32 v52, |v46|, s8, 1.0
	v_fma_f32 v53, |v47|, s8, 1.0
	v_rcp_f32_e32 v52, v52
	v_rcp_f32_e32 v53, v53
	v_pk_mul_f32 v[42:43], v[42:43], v[156:157] op_sel_hi:[1,0]
	s_mov_b32 s4, 0x90000
	v_pk_mul_f32 v[36:37], v[36:37], v[156:157] op_sel_hi:[1,0]
	v_pk_fma_f32 v[56:57], v[52:53], s[10:11], v[40:41] op_sel_hi:[1,0,0]
	v_pk_mul_f32 v[38:39], v[38:39], v[156:157] op_sel_hi:[1,0]
	v_pk_fma_f32 v[56:57], v[52:53], v[56:57], s[14:15] op_sel_hi:[1,1,0]
	v_pk_mul_f32 v[34:35], v[34:35], v[156:157] op_sel_hi:[1,0]
	v_pk_fma_f32 v[56:57], v[52:53], v[56:57], s[36:37] op_sel_hi:[1,1,0]
	s_nop 0
	v_pk_fma_f32 v[56:57], v[52:53], v[56:57], s[66:67] op_sel_hi:[1,1,0]
	s_nop 0
	v_pk_mul_f32 v[52:53], v[52:53], v[56:57]
	v_pk_mul_f32 v[56:57], v[50:51], v[50:51]
	v_pk_mul_f32 v[52:53], v[54:55], v[52:53]
	v_pk_mul_f32 v[56:57], v[56:57], s[20:21] op_sel_hi:[1,0]
	v_pk_mul_f32 v[54:55], v[46:47], v[52:53]
	v_max_f32_e32 v52, 0, v46
	v_max_f32_e32 v53, 0, v47
	v_exp_f32_e32 v56, v56
	v_sub_f32_e64 v46, v52, |v54|
	v_exp_f32_e32 v57, v57
	v_sub_f32_e64 v47, v53, |v55|
	v_fma_f32 v52, |v50|, s8, 1.0
	v_fma_f32 v53, |v51|, s8, 1.0
	v_rcp_f32_e32 v52, v52
	v_rcp_f32_e32 v53, v53
	s_nop 0
	v_pk_fma_f32 v[54:55], v[52:53], s[10:11], v[40:41] op_sel_hi:[1,0,0]
	s_nop 0
	v_pk_fma_f32 v[54:55], v[52:53], v[54:55], s[14:15] op_sel_hi:[1,1,0]
	s_nop 0
	v_pk_fma_f32 v[54:55], v[52:53], v[54:55], s[36:37] op_sel_hi:[1,1,0]
	s_nop 0
	v_pk_fma_f32 v[54:55], v[52:53], v[54:55], s[66:67] op_sel_hi:[1,1,0]
	s_nop 0
	v_pk_mul_f32 v[52:53], v[52:53], v[54:55]
	v_pk_mul_f32 v[54:55], v[42:43], v[42:43]
	v_pk_mul_f32 v[52:53], v[56:57], v[52:53]
	v_pk_mul_f32 v[54:55], v[54:55], s[20:21] op_sel_hi:[1,0]
	v_pk_mul_f32 v[56:57], v[50:51], v[52:53]
	v_max_f32_e32 v52, 0, v50
	v_max_f32_e32 v53, 0, v51
	v_exp_f32_e32 v54, v54
	v_sub_f32_e64 v50, v52, |v56|
	v_exp_f32_e32 v55, v55
	v_sub_f32_e64 v51, v53, |v57|
	v_fma_f32 v52, |v42|, s8, 1.0
	v_fma_f32 v53, |v43|, s8, 1.0
	v_rcp_f32_e32 v52, v52
	v_rcp_f32_e32 v53, v53
	s_nop 0
	v_pk_fma_f32 v[56:57], v[52:53], s[10:11], v[40:41] op_sel_hi:[1,0,0]
	s_nop 0
	v_pk_fma_f32 v[56:57], v[52:53], v[56:57], s[14:15] op_sel_hi:[1,1,0]
	s_nop 0
	v_pk_fma_f32 v[56:57], v[52:53], v[56:57], s[36:37] op_sel_hi:[1,1,0]
	s_nop 0
	v_pk_fma_f32 v[56:57], v[52:53], v[56:57], s[66:67] op_sel_hi:[1,1,0]
	s_nop 0
	v_pk_mul_f32 v[52:53], v[52:53], v[56:57]
	s_nop 0
	v_pk_mul_f32 v[52:53], v[54:55], v[52:53]
	s_nop 0
	v_pk_mul_f32 v[54:55], v[42:43], v[52:53]
	v_max_f32_e32 v52, 0, v42
	v_max_f32_e32 v53, 0, v43
	s_nop 0
	v_sub_f32_e64 v42, v52, |v54|
	v_cvt_pk_bf16_f32 v52, v44, v45
	s_nop 1
	v_sub_f32_e64 v43, v53, |v55|
	v_add_co_u32_e32 v56, vcc, s4, v152
	v_cvt_pk_bf16_f32 v53, v46, v47
	v_cvt_pk_bf16_f32 v54, v50, v51
	v_cvt_pk_bf16_f32 v55, v42, v43
	s_nop 1
	v_addc_co_u32_e32 v57, vcc, 0, v153, vcc
	global_store_dwordx4 v[56:57], v[52:55], off nt
	v_pk_mul_f32 v[56:57], v[36:37], v[36:37]
	s_nop 0
	v_pk_mul_f32 v[52:53], v[32:33], v[156:157] op_sel_hi:[1,0]
	v_fma_f32 v32, |v36|, s8, 1.0
	v_fma_f32 v33, |v37|, s8, 1.0
	v_pk_mul_f32 v[56:57], v[56:57], s[20:21] op_sel_hi:[1,0]
	v_rcp_f32_e32 v32, v32
	v_rcp_f32_e32 v33, v33
	v_exp_f32_e32 v56, v56
	v_exp_f32_e32 v57, v57
; __device__ __forceinline__ unsigned long long f2ss(float v) { return (unsigned long long)(v * 16777216.0f); }
; __device__ __forceinline__ u32x4 pack8(f32x4 v0, f32x4 v1) { u32x4 w; w.x = cvt_pk_bf16(v0[0], v0[1]); w.y = cvt_pk_bf16(v0[2], v0[3]); w.z = cvt_pk_bf16(v1[0], v1[1]); w.w = cvt_pk_bf16(v1[2], v1[3]); return w; }
; __device__ __forceinline__ f32x2 gelu_pk(f32x2 v) {
;     const f32x2 av = __builtin_elementwise_abs(v), d = av * 0.2316418882f + 1.0f;
;     f32x2 t; t.x = __builtin_amdgcn_rcpf(d.x); t.y = __builtin_amdgcn_rcpf(d.y);
;     f32x2 q = t * 0.5307027145f + (-0.7265760135f); q = q * t + 0.7107068705f; q = q * t + (-0.142248368f); q = q * t + 0.127414796f; q = q * t;
;     const f32x2 s = (v * v) * (-0.72134752044f);
;     f32x2 e; e.x = __builtin_amdgcn_exp2f(s.x); e.y = __builtin_amdgcn_exp2f(s.y);
;     const f32x2 m = v * (q * e), r = v - m;
;     f32x2 o; o.x = v.x < 0.f ? m.x : r.x; o.y = v.y < 0.f ? m.y : r.y; return o;
; }
;     __device__ __forceinline__ void operator()(const f32x4 (&acc)[2][2][4][2], const Unit& u, int wr, int wc, int fr, int fq, const Pre& pre) const {
;     ...
;             for (int m = 0; m < 4; ++m) { const int row = row0 + ai * HALF + m * 16; const float r = rs8[ai * 4 + m];
;                 bf16_t* rowp = O + (size_t)row * 2048 + col0; float sq = 0.f;
; #pragma unroll
;                 for (int bj = 0; bj < 2; ++bj) { f32x4 v0 = acc[ai][bj][m][0] * r, v1 = acc[ai][bj][m][1] * r;
;                     f32x2 a = gelu_pk((f32x2){v0[0], v0[1]}), b = gelu_pk((f32x2){v0[2], v0[3]}), c = gelu_pk((f32x2){v1[0], v1[1]}), d = gelu_pk((f32x2){v1[2], v1[3]});
;                     v0 = (f32x4){a.x, a.y, b.x, b.y}; v1 = (f32x4){c.x, c.y, d.x, d.y};
;                     sq += (v0[0] * v0[0] + v0[1] * v0[1]) + (v0[2] * v0[2] + v0[3] * v0[3]) + (v1[0] * v1[0] + v1[1] * v1[1]) + (v1[2] * v1[2] + v1[3] * v1[3]);
;                     *(u32x4*)(rowp + bj * HALF) = pack8(v0, v1); }
;                 if (isv) { sq += __shfl_xor(sq, 16); sq += __shfl_xor(sq, 32); if (fq == 0) atomicAdd(vss + row, f2ss(sq)); } }
	v_pk_fma_f32 v[54:55], v[32:33], s[10:11], v[40:41] op_sel_hi:[1,0,0]
	s_nop 0
	v_pk_fma_f32 v[54:55], v[32:33], v[54:55], s[14:15] op_sel_hi:[1,1,0]
	s_nop 0
	v_pk_fma_f32 v[54:55], v[32:33], v[54:55], s[36:37] op_sel_hi:[1,1,0]
	s_nop 0
	v_pk_fma_f32 v[54:55], v[32:33], v[54:55], s[66:67] op_sel_hi:[1,1,0]
	s_nop 0
	v_pk_mul_f32 v[32:33], v[32:33], v[54:55]
	v_pk_mul_f32 v[54:55], v[38:39], v[38:39]
	v_pk_mul_f32 v[32:33], v[56:57], v[32:33]
	v_pk_mul_f32 v[54:55], v[54:55], s[20:21] op_sel_hi:[1,0]
	v_pk_mul_f32 v[56:57], v[36:37], v[32:33]
	v_max_f32_e32 v32, 0, v36
	v_max_f32_e32 v33, 0, v37
	v_sub_f32_e64 v32, v32, |v56|
	v_fma_f32 v36, |v38|, s8, 1.0
	v_fma_f32 v37, |v39|, s8, 1.0
	v_sub_f32_e64 v33, v33, |v57|
	v_rcp_f32_e32 v36, v36
	v_rcp_f32_e32 v37, v37
	v_exp_f32_e32 v54, v54
	v_exp_f32_e32 v55, v55
	v_pk_fma_f32 v[56:57], v[36:37], s[10:11], v[40:41] op_sel_hi:[1,0,0]
	s_nop 0
	v_pk_fma_f32 v[56:57], v[36:37], v[56:57], s[14:15] op_sel_hi:[1,1,0]
	s_nop 0
	v_pk_fma_f32 v[56:57], v[36:37], v[56:57], s[36:37] op_sel_hi:[1,1,0]
	s_nop 0
	v_pk_fma_f32 v[56:57], v[36:37], v[56:57], s[66:67] op_sel_hi:[1,1,0]
	s_nop 0
	v_pk_mul_f32 v[36:37], v[36:37], v[56:57]
	v_pk_mul_f32 v[56:57], v[52:53], v[52:53]
	v_pk_mul_f32 v[36:37], v[54:55], v[36:37]
	v_pk_mul_f32 v[56:57], v[56:57], s[20:21] op_sel_hi:[1,0]
	v_pk_mul_f32 v[54:55], v[38:39], v[36:37]
	v_max_f32_e32 v36, 0, v38
	v_max_f32_e32 v37, 0, v39
	v_sub_f32_e64 v36, v36, |v54|
	v_fma_f32 v38, |v52|, s8, 1.0
	v_fma_f32 v39, |v53|, s8, 1.0
	v_sub_f32_e64 v37, v37, |v55|
	v_rcp_f32_e32 v38, v38
	v_rcp_f32_e32 v39, v39
	v_exp_f32_e32 v56, v56
	v_exp_f32_e32 v57, v57
	v_pk_fma_f32 v[54:55], v[38:39], s[10:11], v[40:41] op_sel_hi:[1,0,0]
	s_nop 0
	v_pk_fma_f32 v[54:55], v[38:39], v[54:55], s[14:15] op_sel_hi:[1,1,0]
	s_nop 0
	v_pk_fma_f32 v[54:55], v[38:39], v[54:55], s[36:37] op_sel_hi:[1,1,0]
	s_nop 0
	v_pk_fma_f32 v[54:55], v[38:39], v[54:55], s[66:67] op_sel_hi:[1,1,0]
	s_nop 0
	v_pk_mul_f32 v[38:39], v[38:39], v[54:55]
	v_pk_mul_f32 v[54:55], v[34:35], v[34:35]
	v_pk_mul_f32 v[38:39], v[56:57], v[38:39]
	s_nop 0
	v_pk_mul_f32 v[56:57], v[52:53], v[38:39]
	v_max_f32_e32 v38, 0, v52
	v_max_f32_e32 v39, 0, v53
	v_sub_f32_e64 v38, v38, |v56|
	v_fma_f32 v52, |v34|, s8, 1.0
	v_fma_f32 v53, |v35|, s8, 1.0
	v_sub_f32_e64 v39, v39, |v57|
	v_rcp_f32_e32 v52, v52
	v_rcp_f32_e32 v53, v53
	s_nop 0
	v_pk_fma_f32 v[40:41], v[52:53], s[10:11], v[40:41] op_sel_hi:[1,0,0]
	s_nop 0
	v_pk_fma_f32 v[40:41], v[52:53], v[40:41], s[14:15] op_sel_hi:[1,1,0]
	s_nop 0
	v_pk_fma_f32 v[40:41], v[52:53], v[40:41], s[36:37] op_sel_hi:[1,1,0]
	s_nop 0
	v_pk_fma_f32 v[40:41], v[52:53], v[40:41], s[66:67] op_sel_hi:[1,1,0]
	s_nop 0
	v_pk_mul_f32 v[40:41], v[52:53], v[40:41]
	v_pk_mul_f32 v[52:53], v[54:55], s[20:21] op_sel_hi:[1,0]
	s_nop 0
	v_exp_f32_e32 v52, v52
	v_exp_f32_e32 v53, v53
	s_nop 0
	v_pk_mul_f32 v[40:41], v[52:53], v[40:41]
	s_nop 0
	v_pk_mul_f32 v[52:53], v[34:35], v[40:41]
	v_max_f32_e32 v40, 0, v34
	v_max_f32_e32 v41, 0, v35
	s_nop 0
	v_sub_f32_e64 v34, v40, |v52|
	v_cvt_pk_bf16_f32 v52, v32, v33
	s_nop 1
	v_sub_f32_e64 v35, v41, |v53|
	s_and_b64 vcc, exec, s[44:45]
	v_cvt_pk_bf16_f32 v53, v36, v37
	v_cvt_pk_bf16_f32 v54, v38, v39
	v_cvt_pk_bf16_f32 v55, v34, v35
	global_store_dwordx4 v[48:49], v[52:55], off offset:256 nt
	s_cbranch_vccnz .LBB0_81
	v_mul_f32_e32 v40, v43, v43
	v_mul_f32_e32 v33, v33, v33
	v_fmac_f32_e32 v40, v42, v42
	v_mul_f32_e32 v41, v45, v45
	v_mul_f32_e32 v42, v47, v47
	v_fmac_f32_e32 v33, v32, v32
	v_mul_f32_e32 v32, v37, v37
	v_fmac_f32_e32 v41, v44, v44
	v_fmac_f32_e32 v42, v46, v46
	v_fmac_f32_e32 v32, v36, v36
	v_add_f32_e32 v41, v41, v42
	v_mul_f32_e32 v42, v51, v51
	v_add_f32_e32 v32, v33, v32
	v_mul_f32_e32 v33, v39, v39
	v_fmac_f32_e32 v42, v50, v50
	v_mul_f32_e32 v35, v35, v35
	v_fmac_f32_e32 v33, v38, v38
	v_add_f32_e32 v41, v42, v41
	v_fmac_f32_e32 v35, v34, v34
	v_add_f32_e32 v32, v33, v32
	v_add_f32_e32 v40, v40, v41
	v_add_f32_e32 v32, v35, v32
	v_add_f32_e32 v32, v40, v32
	ds_bpermute_b32 v33, v147, v32
	s_waitcnt lgkmcnt(0)
	v_add_f32_e32 v32, v32, v33
	ds_bpermute_b32 v33, v165, v32
	s_and_saveexec_b64 s[26:27], s[40:41]
	s_cbranch_execz .LBB0_80
	s_waitcnt lgkmcnt(0)
	v_add_f32_e32 v32, v32, v33
	v_mul_f32_e32 v32, 0x4b800000, v32
	v_trunc_f32_e32 v32, v32
	v_mul_f32_e32 v33, 0x2f800000, v32
	v_floor_f32_e32 v33, v33
	v_fmac_f32_e32 v32, 0xcf800000, v33
	v_cvt_u32_f32_e32 v32, v32
	v_cvt_u32_f32_e32 v33, v33
	v_lshl_add_u64 v[34:35], v[142:143], 3, s[52:53]
	global_atomic_add_x2 v[34:35], v[32:33], off offset:1152

; __device__ __forceinline__ unsigned long long f2ss(float v) { return (unsigned long long)(v * 16777216.0f); }
; __device__ __forceinline__ u32x4 pack8(f32x4 v0, f32x4 v1) { u32x4 w; w.x = cvt_pk_bf16(v0[0], v0[1]); w.y = cvt_pk_bf16(v0[2], v0[3]); w.z = cvt_pk_bf16(v1[0], v1[1]); w.w = cvt_pk_bf16(v1[2], v1[3]); return w; }
; __device__ __forceinline__ f32x2 gelu_pk(f32x2 v) {
;     const f32x2 av = __builtin_elementwise_abs(v), d = av * 0.2316418882f + 1.0f;
;     f32x2 t; t.x = __builtin_amdgcn_rcpf(d.x); t.y = __builtin_amdgcn_rcpf(d.y);
;     f32x2 q = t * 0.5307027145f + (-0.7265760135f); q = q * t + 0.7107068705f; q = q * t + (-0.142248368f); q = q * t + 0.127414796f; q = q * t;
;     const f32x2 s = (v * v) * (-0.72134752044f);
;     f32x2 e; e.x = __builtin_amdgcn_exp2f(s.x); e.y = __builtin_amdgcn_exp2f(s.y);
;     const f32x2 m = v * (q * e), r = v - m;
;     f32x2 o; o.x = v.x < 0.f ? m.x : r.x; o.y = v.y < 0.f ? m.y : r.y; return o;
; }
;     __device__ __forceinline__ void operator()(const f32x4 (&acc)[2][2][4][2], const Unit& u, int wr, int wc, int fr, int fq, const Pre& pre) const {
;     ...
;             for (int m = 0; m < 4; ++m) { const int row = row0 + ai * HALF + m * 16; const float r = rs8[ai * 4 + m];
;                 bf16_t* rowp = O + (size_t)row * 2048 + col0; float sq = 0.f;
; #pragma unroll
;                 for (int bj = 0; bj < 2; ++bj) { f32x4 v0 = acc[ai][bj][m][0] * r, v1 = acc[ai][bj][m][1] * r;
;                     f32x2 a = gelu_pk((f32x2){v0[0], v0[1]}), b = gelu_pk((f32x2){v0[2], v0[3]}), c = gelu_pk((f32x2){v1[0], v1[1]}), d = gelu_pk((f32x2){v1[2], v1[3]});
;                     v0 = (f32x4){a.x, a.y, b.x, b.y}; v1 = (f32x4){c.x, c.y, d.x, d.y};
;                     sq += (v0[0] * v0[0] + v0[1] * v0[1]) + (v0[2] * v0[2] + v0[3] * v0[3]) + (v1[0] * v1[0] + v1[1] * v1[1]) + (v1[2] * v1[2] + v1[3] * v1[3]);
;                     *(u32x4*)(rowp + bj * HALF) = pack8(v0, v1); }
;                 if (isv) { sq += __shfl_xor(sq, 16); sq += __shfl_xor(sq, 32); if (fq == 0) atomicAdd(vss + row, f2ss(sq)); } }
.LBB0_81:
	v_pk_mul_f32 v[28:29], v[28:29], v[154:155] op_sel_hi:[1,0]
	v_pk_mul_f32 v[34:35], v[24:25], v[154:155] op_sel_hi:[1,0]
	v_fma_f32 v24, |v28|, s8, 1.0
	v_fma_f32 v25, |v29|, s8, 1.0
	s_mov_b64 s[20:21], 0xa0000
	v_rcp_f32_e32 v36, v24
	v_rcp_f32_e32 v37, v25
	s_waitcnt lgkmcnt(0)
	v_lshl_add_u64 v[32:33], v[152:153], 0, s[20:21]
	v_mov_b64_e32 v[24:25], s[12:13]
	v_pk_mul_f32 v[40:41], v[28:29], v[28:29]
	s_mov_b32 s20, 0xbf38aa3b
	v_pk_fma_f32 v[38:39], v[36:37], s[10:11], v[24:25] op_sel_hi:[1,0,0]
	v_pk_mul_f32 v[40:41], v[40:41], s[20:21] op_sel_hi:[1,0]
	v_pk_fma_f32 v[38:39], v[36:37], v[38:39], s[14:15] op_sel_hi:[1,1,0]
	v_exp_f32_e32 v40, v40
	v_exp_f32_e32 v41, v41
	v_pk_fma_f32 v[38:39], v[36:37], v[38:39], s[36:37] op_sel_hi:[1,1,0]
	s_nop 0
	v_pk_fma_f32 v[38:39], v[36:37], v[38:39], s[66:67] op_sel_hi:[1,1,0]
	v_pk_mul_f32 v[30:31], v[30:31], v[154:155] op_sel_hi:[1,0]
	v_pk_mul_f32 v[36:37], v[36:37], v[38:39]
	v_pk_mul_f32 v[38:39], v[30:31], v[30:31]
	v_pk_mul_f32 v[36:37], v[40:41], v[36:37]
	v_pk_mul_f32 v[38:39], v[38:39], s[20:21] op_sel_hi:[1,0]
	v_pk_mul_f32 v[40:41], v[28:29], v[36:37]
	v_max_f32_e32 v36, 0, v28
	v_max_f32_e32 v37, 0, v29
	v_exp_f32_e32 v38, v38
	v_sub_f32_e64 v28, v36, |v40|
	v_exp_f32_e32 v39, v39
	v_sub_f32_e64 v29, v37, |v41|
	v_fma_f32 v36, |v30|, s8, 1.0
	v_fma_f32 v37, |v31|, s8, 1.0
	v_rcp_f32_e32 v36, v36
	v_rcp_f32_e32 v37, v37
	v_pk_mul_f32 v[26:27], v[26:27], v[154:155] op_sel_hi:[1,0]
	s_mov_b32 s4, 0xa0000
	v_pk_mul_f32 v[20:21], v[20:21], v[154:155] op_sel_hi:[1,0]
	v_pk_fma_f32 v[40:41], v[36:37], s[10:11], v[24:25] op_sel_hi:[1,0,0]
	v_pk_mul_f32 v[22:23], v[22:23], v[154:155] op_sel_hi:[1,0]
	v_pk_fma_f32 v[40:41], v[36:37], v[40:41], s[14:15] op_sel_hi:[1,1,0]
	v_pk_mul_f32 v[18:19], v[18:19], v[154:155] op_sel_hi:[1,0]
	v_pk_fma_f32 v[40:41], v[36:37], v[40:41], s[36:37] op_sel_hi:[1,1,0]
	s_nop 0
	v_pk_fma_f32 v[40:41], v[36:37], v[40:41], s[66:67] op_sel_hi:[1,1,0]
	s_nop 0
	v_pk_mul_f32 v[36:37], v[36:37], v[40:41]
	v_pk_mul_f32 v[40:41], v[34:35], v[34:35]
	v_pk_mul_f32 v[36:37], v[38:39], v[36:37]
	v_pk_mul_f32 v[40:41], v[40:41], s[20:21] op_sel_hi:[1,0]
	v_pk_mul_f32 v[38:39], v[30:31], v[36:37]
	v_max_f32_e32 v36, 0, v30
	v_max_f32_e32 v37, 0, v31
	v_exp_f32_e32 v40, v40
	v_sub_f32_e64 v30, v36, |v38|
	v_exp_f32_e32 v41, v41
	v_sub_f32_e64 v31, v37, |v39|
	v_fma_f32 v36, |v34|, s8, 1.0
	v_fma_f32 v37, |v35|, s8, 1.0
	v_rcp_f32_e32 v36, v36
	v_rcp_f32_e32 v37, v37
	s_nop 0
	v_pk_fma_f32 v[38:39], v[36:37], s[10:11], v[24:25] op_sel_hi:[1,0,0]
	s_nop 0
	v_pk_fma_f32 v[38:39], v[36:37], v[38:39], s[14:15] op_sel_hi:[1,1,0]
	s_nop 0
	v_pk_fma_f32 v[38:39], v[36:37], v[38:39], s[36:37] op_sel_hi:[1,1,0]
	s_nop 0
	v_pk_fma_f32 v[38:39], v[36:37], v[38:39], s[66:67] op_sel_hi:[1,1,0]
	s_nop 0
	v_pk_mul_f32 v[36:37], v[36:37], v[38:39]
	v_pk_mul_f32 v[38:39], v[26:27], v[26:27]
	v_pk_mul_f32 v[36:37], v[40:41], v[36:37]
	v_pk_mul_f32 v[38:39], v[38:39], s[20:21] op_sel_hi:[1,0]
	v_pk_mul_f32 v[40:41], v[34:35], v[36:37]
	v_max_f32_e32 v36, 0, v34
	v_max_f32_e32 v37, 0, v35
	v_exp_f32_e32 v38, v38
	v_sub_f32_e64 v34, v36, |v40|
	v_exp_f32_e32 v39, v39
	v_sub_f32_e64 v35, v37, |v41|
	v_fma_f32 v36, |v26|, s8, 1.0
	v_fma_f32 v37, |v27|, s8, 1.0
	v_rcp_f32_e32 v36, v36
	v_rcp_f32_e32 v37, v37
	s_nop 0
	v_pk_fma_f32 v[40:41], v[36:37], s[10:11], v[24:25] op_sel_hi:[1,0,0]
	s_nop 0
	v_pk_fma_f32 v[40:41], v[36:37], v[40:41], s[14:15] op_sel_hi:[1,1,0]
	s_nop 0
	v_pk_fma_f32 v[40:41], v[36:37], v[40:41], s[36:37] op_sel_hi:[1,1,0]
	s_nop 0
	v_pk_fma_f32 v[40:41], v[36:37], v[40:41], s[66:67] op_sel_hi:[1,1,0]
	s_nop 0
	v_pk_mul_f32 v[36:37], v[36:37], v[40:41]
	s_nop 0
	v_pk_mul_f32 v[36:37], v[38:39], v[36:37]
	s_nop 0
	v_pk_mul_f32 v[38:39], v[26:27], v[36:37]
	v_max_f32_e32 v36, 0, v26
	v_max_f32_e32 v37, 0, v27
	s_nop 0
	v_sub_f32_e64 v26, v36, |v38|
	v_cvt_pk_bf16_f32 v36, v28, v29
	s_nop 1
	v_sub_f32_e64 v27, v37, |v39|
	v_add_co_u32_e32 v40, vcc, s4, v152
	v_cvt_pk_bf16_f32 v37, v30, v31
	v_cvt_pk_bf16_f32 v38, v34, v35
	v_cvt_pk_bf16_f32 v39, v26, v27
	s_nop 1
	v_addc_co_u32_e32 v41, vcc, 0, v153, vcc
	global_store_dwordx4 v[40:41], v[36:39], off nt
	v_pk_mul_f32 v[40:41], v[20:21], v[20:21]
	s_nop 0
	v_pk_mul_f32 v[36:37], v[16:17], v[154:155] op_sel_hi:[1,0]
	v_fma_f32 v16, |v20|, s8, 1.0
	v_fma_f32 v17, |v21|, s8, 1.0
	v_pk_mul_f32 v[40:41], v[40:41], s[20:21] op_sel_hi:[1,0]
	v_rcp_f32_e32 v16, v16
	v_rcp_f32_e32 v17, v17
	v_exp_f32_e32 v40, v40
	v_exp_f32_e32 v41, v41
; __device__ __forceinline__ unsigned long long f2ss(float v) { return (unsigned long long)(v * 16777216.0f); }
; __device__ __forceinline__ u32x4 pack8(f32x4 v0, f32x4 v1) { u32x4 w; w.x = cvt_pk_bf16(v0[0], v0[1]); w.y = cvt_pk_bf16(v0[2], v0[3]); w.z = cvt_pk_bf16(v1[0], v1[1]); w.w = cvt_pk_bf16(v1[2], v1[3]); return w; }
; __device__ __forceinline__ f32x2 gelu_pk(f32x2 v) {
;     const f32x2 av = __builtin_elementwise_abs(v), d = av * 0.2316418882f + 1.0f;
;     f32x2 t; t.x = __builtin_amdgcn_rcpf(d.x); t.y = __builtin_amdgcn_rcpf(d.y);
;     f32x2 q = t * 0.5307027145f + (-0.7265760135f); q = q * t + 0.7107068705f; q = q * t + (-0.142248368f); q = q * t + 0.127414796f; q = q * t;
;     const f32x2 s = (v * v) * (-0.72134752044f);
;     f32x2 e; e.x = __builtin_amdgcn_exp2f(s.x); e.y = __builtin_amdgcn_exp2f(s.y);
;     const f32x2 m = v * (q * e), r = v - m;
;     f32x2 o; o.x = v.x < 0.f ? m.x : r.x; o.y = v.y < 0.f ? m.y : r.y; return o;
; }
;     __device__ __forceinline__ void operator()(const f32x4 (&acc)[2][2][4][2], const Unit& u, int wr, int wc, int fr, int fq, const Pre& pre) const {
;     ...
;             for (int m = 0; m < 4; ++m) { const int row = row0 + ai * HALF + m * 16; const float r = rs8[ai * 4 + m];
;                 bf16_t* rowp = O + (size_t)row * 2048 + col0; float sq = 0.f;
; #pragma unroll
;                 for (int bj = 0; bj < 2; ++bj) { f32x4 v0 = acc[ai][bj][m][0] * r, v1 = acc[ai][bj][m][1] * r;
;                     f32x2 a = gelu_pk((f32x2){v0[0], v0[1]}), b = gelu_pk((f32x2){v0[2], v0[3]}), c = gelu_pk((f32x2){v1[0], v1[1]}), d = gelu_pk((f32x2){v1[2], v1[3]});
;                     v0 = (f32x4){a.x, a.y, b.x, b.y}; v1 = (f32x4){c.x, c.y, d.x, d.y};
;                     sq += (v0[0] * v0[0] + v0[1] * v0[1]) + (v0[2] * v0[2] + v0[3] * v0[3]) + (v1[0] * v1[0] + v1[1] * v1[1]) + (v1[2] * v1[2] + v1[3] * v1[3]);
;                     *(u32x4*)(rowp + bj * HALF) = pack8(v0, v1); }
;                 if (isv) { sq += __shfl_xor(sq, 16); sq += __shfl_xor(sq, 32); if (fq == 0) atomicAdd(vss + row, f2ss(sq)); } }
	v_pk_fma_f32 v[38:39], v[16:17], s[10:11], v[24:25] op_sel_hi:[1,0,0]
	s_nop 0
	v_pk_fma_f32 v[38:39], v[16:17], v[38:39], s[14:15] op_sel_hi:[1,1,0]
	s_nop 0
	v_pk_fma_f32 v[38:39], v[16:17], v[38:39], s[36:37] op_sel_hi:[1,1,0]
	s_nop 0
	v_pk_fma_f32 v[38:39], v[16:17], v[38:39], s[66:67] op_sel_hi:[1,1,0]
	s_nop 0
	v_pk_mul_f32 v[16:17], v[16:17], v[38:39]
	v_pk_mul_f32 v[38:39], v[22:23], v[22:23]
	v_pk_mul_f32 v[16:17], v[40:41], v[16:17]
	v_pk_mul_f32 v[38:39], v[38:39], s[20:21] op_sel_hi:[1,0]
	v_pk_mul_f32 v[40:41], v[20:21], v[16:17]
	v_max_f32_e32 v16, 0, v20
	v_max_f32_e32 v17, 0, v21
	v_sub_f32_e64 v16, v16, |v40|
	v_fma_f32 v20, |v22|, s8, 1.0
	v_fma_f32 v21, |v23|, s8, 1.0
	v_sub_f32_e64 v17, v17, |v41|
	v_rcp_f32_e32 v20, v20
	v_rcp_f32_e32 v21, v21
	v_exp_f32_e32 v38, v38
	v_exp_f32_e32 v39, v39
	v_pk_fma_f32 v[40:41], v[20:21], s[10:11], v[24:25] op_sel_hi:[1,0,0]
	s_nop 0
	v_pk_fma_f32 v[40:41], v[20:21], v[40:41], s[14:15] op_sel_hi:[1,1,0]
	s_nop 0
	v_pk_fma_f32 v[40:41], v[20:21], v[40:41], s[36:37] op_sel_hi:[1,1,0]
	s_nop 0
	v_pk_fma_f32 v[40:41], v[20:21], v[40:41], s[66:67] op_sel_hi:[1,1,0]
	s_nop 0
	v_pk_mul_f32 v[20:21], v[20:21], v[40:41]
	v_pk_mul_f32 v[40:41], v[36:37], v[36:37]
	v_pk_mul_f32 v[20:21], v[38:39], v[20:21]
	v_pk_mul_f32 v[40:41], v[40:41], s[20:21] op_sel_hi:[1,0]
	v_pk_mul_f32 v[38:39], v[22:23], v[20:21]
	v_max_f32_e32 v20, 0, v22
	v_max_f32_e32 v21, 0, v23
	v_sub_f32_e64 v20, v20, |v38|
	v_fma_f32 v22, |v36|, s8, 1.0
	v_fma_f32 v23, |v37|, s8, 1.0
	v_sub_f32_e64 v21, v21, |v39|
	v_rcp_f32_e32 v22, v22
	v_rcp_f32_e32 v23, v23
	v_exp_f32_e32 v40, v40
	v_exp_f32_e32 v41, v41
	v_pk_fma_f32 v[38:39], v[22:23], s[10:11], v[24:25] op_sel_hi:[1,0,0]
	s_nop 0
	v_pk_fma_f32 v[38:39], v[22:23], v[38:39], s[14:15] op_sel_hi:[1,1,0]
	s_nop 0
	v_pk_fma_f32 v[38:39], v[22:23], v[38:39], s[36:37] op_sel_hi:[1,1,0]
	s_nop 0
	v_pk_fma_f32 v[38:39], v[22:23], v[38:39], s[66:67] op_sel_hi:[1,1,0]
	s_nop 0
	v_pk_mul_f32 v[22:23], v[22:23], v[38:39]
	v_pk_mul_f32 v[38:39], v[18:19], v[18:19]
	v_pk_mul_f32 v[22:23], v[40:41], v[22:23]
	s_nop 0
	v_pk_mul_f32 v[40:41], v[36:37], v[22:23]
	v_max_f32_e32 v22, 0, v36
	v_max_f32_e32 v23, 0, v37
	v_sub_f32_e64 v22, v22, |v40|
	v_fma_f32 v36, |v18|, s8, 1.0
	v_fma_f32 v37, |v19|, s8, 1.0
	v_sub_f32_e64 v23, v23, |v41|
	v_rcp_f32_e32 v36, v36
	v_rcp_f32_e32 v37, v37
	s_nop 0
	v_pk_fma_f32 v[24:25], v[36:37], s[10:11], v[24:25] op_sel_hi:[1,0,0]
	s_nop 0
	v_pk_fma_f32 v[24:25], v[36:37], v[24:25], s[14:15] op_sel_hi:[1,1,0]
	s_nop 0
	v_pk_fma_f32 v[24:25], v[36:37], v[24:25], s[36:37] op_sel_hi:[1,1,0]
	s_nop 0
	v_pk_fma_f32 v[24:25], v[36:37], v[24:25], s[66:67] op_sel_hi:[1,1,0]
	s_nop 0
	v_pk_mul_f32 v[24:25], v[36:37], v[24:25]
	v_pk_mul_f32 v[36:37], v[38:39], s[20:21] op_sel_hi:[1,0]
	s_nop 0
	v_exp_f32_e32 v36, v36
	v_exp_f32_e32 v37, v37
	s_nop 0
	v_pk_mul_f32 v[24:25], v[36:37], v[24:25]
	s_nop 0
	v_pk_mul_f32 v[36:37], v[18:19], v[24:25]
	v_max_f32_e32 v24, 0, v18
	v_max_f32_e32 v25, 0, v19
	s_nop 0
	v_sub_f32_e64 v18, v24, |v36|
	v_cvt_pk_bf16_f32 v36, v16, v17
	s_nop 1
	v_sub_f32_e64 v19, v25, |v37|
	s_and_b64 vcc, exec, s[44:45]
	v_cvt_pk_bf16_f32 v37, v20, v21
	v_cvt_pk_bf16_f32 v38, v22, v23
	v_cvt_pk_bf16_f32 v39, v18, v19
	global_store_dwordx4 v[32:33], v[36:39], off offset:256 nt
	s_cbranch_vccnz .LBB0_85
	v_mul_f32_e32 v24, v27, v27
	v_mul_f32_e32 v17, v17, v17
	v_fmac_f32_e32 v24, v26, v26
	v_mul_f32_e32 v25, v29, v29
	v_mul_f32_e32 v26, v31, v31
	v_fmac_f32_e32 v17, v16, v16
	v_mul_f32_e32 v16, v21, v21
	v_fmac_f32_e32 v25, v28, v28
	v_fmac_f32_e32 v26, v30, v30
	v_fmac_f32_e32 v16, v20, v20
	v_add_f32_e32 v25, v25, v26
	v_mul_f32_e32 v26, v35, v35
	v_add_f32_e32 v16, v17, v16
	v_mul_f32_e32 v17, v23, v23
	v_fmac_f32_e32 v26, v34, v34
	v_mul_f32_e32 v19, v19, v19
	v_fmac_f32_e32 v17, v22, v22
	v_add_f32_e32 v25, v26, v25
	v_fmac_f32_e32 v19, v18, v18
	v_add_f32_e32 v16, v17, v16
	v_add_f32_e32 v24, v24, v25
	v_add_f32_e32 v16, v19, v16
	v_add_f32_e32 v16, v24, v16
	ds_bpermute_b32 v17, v147, v16
	s_waitcnt lgkmcnt(0)
	v_add_f32_e32 v16, v16, v17
	ds_bpermute_b32 v17, v165, v16
	s_and_saveexec_b64 s[26:27], s[40:41]
	s_cbranch_execz .LBB0_84
	s_waitcnt lgkmcnt(0)
	v_add_f32_e32 v16, v16, v17
	v_mul_f32_e32 v16, 0x4b800000, v16
	v_trunc_f32_e32 v16, v16
	v_mul_f32_e32 v17, 0x2f800000, v16
	v_floor_f32_e32 v17, v17
	v_fmac_f32_e32 v16, 0xcf800000, v17
	v_cvt_u32_f32_e32 v16, v16
	v_cvt_u32_f32_e32 v17, v17
	v_lshl_add_u64 v[18:19], v[142:143], 3, s[52:53]
	global_atomic_add_x2 v[18:19], v[16:17], off offset:1280

; __device__ __forceinline__ u32x4 pack8(f32x4 v0, f32x4 v1) { u32x4 w; w.x = cvt_pk_bf16(v0[0], v0[1]); w.y = cvt_pk_bf16(v0[2], v0[3]); w.z = cvt_pk_bf16(v1[0], v1[1]); w.w = cvt_pk_bf16(v1[2], v1[3]); return w; }
; __device__ __forceinline__ f32x2 gelu_pk(f32x2 v) {
;     const f32x2 av = __builtin_elementwise_abs(v), d = av * 0.2316418882f + 1.0f;
;     f32x2 t; t.x = __builtin_amdgcn_rcpf(d.x); t.y = __builtin_amdgcn_rcpf(d.y);
;     f32x2 q = t * 0.5307027145f + (-0.7265760135f); q = q * t + 0.7107068705f; q = q * t + (-0.142248368f); q = q * t + 0.127414796f; q = q * t;
;     const f32x2 s = (v * v) * (-0.72134752044f);
;     f32x2 e; e.x = __builtin_amdgcn_exp2f(s.x); e.y = __builtin_amdgcn_exp2f(s.y);
;     const f32x2 m = v * (q * e), r = v - m;
;     f32x2 o; o.x = v.x < 0.f ? m.x : r.x; o.y = v.y < 0.f ? m.y : r.y; return o;
; }
;     __device__ __forceinline__ void operator()(const f32x4 (&acc)[2][2][4][2], const Unit& u, int wr, int wc, int fr, int fq, const Pre& pre) const {
;     ...
;                 for (int bj = 0; bj < 2; ++bj) { f32x4 v0 = acc[ai][bj][m][0] * r, v1 = acc[ai][bj][m][1] * r;
;                     f32x2 a = gelu_pk((f32x2){v0[0], v0[1]}), b = gelu_pk((f32x2){v0[2], v0[3]}), c = gelu_pk((f32x2){v1[0], v1[1]}), d = gelu_pk((f32x2){v1[2], v1[3]});
;                     v0 = (f32x4){a.x, a.y, b.x, b.y}; v1 = (f32x4){c.x, c.y, d.x, d.y};
;                     sq += (v0[0] * v0[0] + v0[1] * v0[1]) + (v0[2] * v0[2] + v0[3] * v0[3]) + (v1[0] * v1[0] + v1[1] * v1[1]) + (v1[2] * v1[2] + v1[3] * v1[3]);
;                     *(u32x4*)(rowp + bj * HALF) = pack8(v0, v1); }
.LBB0_85:
	v_pk_mul_f32 v[12:13], v[12:13], v[146:147] op_sel_hi:[1,0]
	v_pk_mul_f32 v[18:19], v[8:9], v[146:147] op_sel_hi:[1,0]
	v_fma_f32 v8, |v12|, s8, 1.0
	v_fma_f32 v9, |v13|, s8, 1.0
	v_pk_mul_f32 v[24:25], v[12:13], v[12:13]
	v_rcp_f32_e32 v20, v8
	v_rcp_f32_e32 v21, v9
	v_mov_b64_e32 v[8:9], s[12:13]
	s_mov_b32 s12, 0xbf38aa3b
	v_pk_mul_f32 v[24:25], v[24:25], s[12:13] op_sel_hi:[1,0]
	v_pk_fma_f32 v[22:23], v[20:21], s[10:11], v[8:9] op_sel_hi:[1,0,0]
	v_exp_f32_e32 v24, v24
	v_pk_fma_f32 v[22:23], v[20:21], v[22:23], s[14:15] op_sel_hi:[1,1,0]
	v_exp_f32_e32 v25, v25
	v_pk_fma_f32 v[22:23], v[20:21], v[22:23], s[36:37] op_sel_hi:[1,1,0]
	s_nop 0
	v_pk_fma_f32 v[22:23], v[20:21], v[22:23], s[66:67] op_sel_hi:[1,1,0]
	v_pk_mul_f32 v[14:15], v[14:15], v[146:147] op_sel_hi:[1,0]
	v_pk_mul_f32 v[20:21], v[20:21], v[22:23]
	v_pk_mul_f32 v[22:23], v[14:15], v[14:15]
	v_pk_mul_f32 v[20:21], v[24:25], v[20:21]
	v_pk_mul_f32 v[22:23], v[22:23], s[12:13] op_sel_hi:[1,0]
	v_pk_mul_f32 v[24:25], v[12:13], v[20:21]
	v_max_f32_e32 v20, 0, v12
	v_max_f32_e32 v21, 0, v13
	v_exp_f32_e32 v22, v22
	v_sub_f32_e64 v12, v20, |v24|
	v_exp_f32_e32 v23, v23
	v_sub_f32_e64 v13, v21, |v25|
	v_fma_f32 v20, |v14|, s8, 1.0
	v_fma_f32 v21, |v15|, s8, 1.0
	v_rcp_f32_e32 v20, v20
	v_rcp_f32_e32 v21, v21
	v_pk_mul_f32 v[10:11], v[10:11], v[146:147] op_sel_hi:[1,0]
	s_mov_b32 s4, 0xb0000
	v_pk_mul_f32 v[4:5], v[4:5], v[146:147] op_sel_hi:[1,0]
	v_pk_fma_f32 v[24:25], v[20:21], s[10:11], v[8:9] op_sel_hi:[1,0,0]
	v_pk_mul_f32 v[6:7], v[6:7], v[146:147] op_sel_hi:[1,0]
	v_pk_fma_f32 v[24:25], v[20:21], v[24:25], s[14:15] op_sel_hi:[1,1,0]
	v_pk_mul_f32 v[2:3], v[2:3], v[146:147] op_sel_hi:[1,0]
	v_pk_fma_f32 v[24:25], v[20:21], v[24:25], s[36:37] op_sel_hi:[1,1,0]
	s_mov_b64 s[20:21], 0xb0000
	v_pk_fma_f32 v[24:25], v[20:21], v[24:25], s[66:67] op_sel_hi:[1,1,0]
	s_waitcnt lgkmcnt(0)
; __device__ __forceinline__ unsigned long long f2ss(float v) { return (unsigned long long)(v * 16777216.0f); }
; __device__ __forceinline__ u32x4 pack8(f32x4 v0, f32x4 v1) { u32x4 w; w.x = cvt_pk_bf16(v0[0], v0[1]); w.y = cvt_pk_bf16(v0[2], v0[3]); w.z = cvt_pk_bf16(v1[0], v1[1]); w.w = cvt_pk_bf16(v1[2], v1[3]); return w; }
; __device__ __forceinline__ f32x2 gelu_pk(f32x2 v) {
;     const f32x2 av = __builtin_elementwise_abs(v), d = av * 0.2316418882f + 1.0f;
;     f32x2 t; t.x = __builtin_amdgcn_rcpf(d.x); t.y = __builtin_amdgcn_rcpf(d.y);
;     f32x2 q = t * 0.5307027145f + (-0.7265760135f); q = q * t + 0.7107068705f; q = q * t + (-0.142248368f); q = q * t + 0.127414796f; q = q * t;
;     const f32x2 s = (v * v) * (-0.72134752044f);
;     f32x2 e; e.x = __builtin_amdgcn_exp2f(s.x); e.y = __builtin_amdgcn_exp2f(s.y);
;     const f32x2 m = v * (q * e), r = v - m;
;     f32x2 o; o.x = v.x < 0.f ? m.x : r.x; o.y = v.y < 0.f ? m.y : r.y; return o;
; }
;     __device__ __forceinline__ void operator()(const f32x4 (&acc)[2][2][4][2], const Unit& u, int wr, int wc, int fr, int fq, const Pre& pre) const {
;     ...
;                 for (int bj = 0; bj < 2; ++bj) { f32x4 v0 = acc[ai][bj][m][0] * r, v1 = acc[ai][bj][m][1] * r;
;                     f32x2 a = gelu_pk((f32x2){v0[0], v0[1]}), b = gelu_pk((f32x2){v0[2], v0[3]}), c = gelu_pk((f32x2){v1[0], v1[1]}), d = gelu_pk((f32x2){v1[2], v1[3]});
;                     v0 = (f32x4){a.x, a.y, b.x, b.y}; v1 = (f32x4){c.x, c.y, d.x, d.y};
;                     sq += (v0[0] * v0[0] + v0[1] * v0[1]) + (v0[2] * v0[2] + v0[3] * v0[3]) + (v1[0] * v1[0] + v1[1] * v1[1]) + (v1[2] * v1[2] + v1[3] * v1[3]);
;                     *(u32x4*)(rowp + bj * HALF) = pack8(v0, v1); }
;                 if (isv) { sq += __shfl_xor(sq, 16); sq += __shfl_xor(sq, 32); if (fq == 0) atomicAdd(vss + row, f2ss(sq)); } }
	v_lshl_add_u64 v[16:17], v[152:153], 0, s[20:21]
	v_pk_mul_f32 v[20:21], v[20:21], v[24:25]
	v_pk_mul_f32 v[24:25], v[18:19], v[18:19]
	v_pk_mul_f32 v[20:21], v[22:23], v[20:21]
	v_pk_mul_f32 v[24:25], v[24:25], s[12:13] op_sel_hi:[1,0]
	v_pk_mul_f32 v[22:23], v[14:15], v[20:21]
	v_max_f32_e32 v20, 0, v14
	v_max_f32_e32 v21, 0, v15
	v_exp_f32_e32 v24, v24
	v_sub_f32_e64 v14, v20, |v22|
	v_exp_f32_e32 v25, v25
	v_sub_f32_e64 v15, v21, |v23|
	v_fma_f32 v20, |v18|, s8, 1.0
	v_fma_f32 v21, |v19|, s8, 1.0
	v_rcp_f32_e32 v20, v20
	v_rcp_f32_e32 v21, v21
	s_nop 0
	v_pk_fma_f32 v[22:23], v[20:21], s[10:11], v[8:9] op_sel_hi:[1,0,0]
	s_nop 0
	v_pk_fma_f32 v[22:23], v[20:21], v[22:23], s[14:15] op_sel_hi:[1,1,0]
	s_nop 0
	v_pk_fma_f32 v[22:23], v[20:21], v[22:23], s[36:37] op_sel_hi:[1,1,0]
	s_nop 0
	v_pk_fma_f32 v[22:23], v[20:21], v[22:23], s[66:67] op_sel_hi:[1,1,0]
	s_nop 0
	v_pk_mul_f32 v[20:21], v[20:21], v[22:23]
	v_pk_mul_f32 v[22:23], v[10:11], v[10:11]
	v_pk_mul_f32 v[20:21], v[24:25], v[20:21]
	v_pk_mul_f32 v[22:23], v[22:23], s[12:13] op_sel_hi:[1,0]
	v_pk_mul_f32 v[24:25], v[18:19], v[20:21]
	v_max_f32_e32 v20, 0, v18
	v_max_f32_e32 v21, 0, v19
	v_exp_f32_e32 v22, v22
	v_sub_f32_e64 v18, v20, |v24|
	v_exp_f32_e32 v23, v23
	v_sub_f32_e64 v19, v21, |v25|
	v_fma_f32 v20, |v10|, s8, 1.0
	v_fma_f32 v21, |v11|, s8, 1.0
	v_rcp_f32_e32 v20, v20
	v_rcp_f32_e32 v21, v21
	s_nop 0
	v_pk_fma_f32 v[24:25], v[20:21], s[10:11], v[8:9] op_sel_hi:[1,0,0]
	s_nop 0
	v_pk_fma_f32 v[24:25], v[20:21], v[24:25], s[14:15] op_sel_hi:[1,1,0]
	s_nop 0
	v_pk_fma_f32 v[24:25], v[20:21], v[24:25], s[36:37] op_sel_hi:[1,1,0]
	s_nop 0
	v_pk_fma_f32 v[24:25], v[20:21], v[24:25], s[66:67] op_sel_hi:[1,1,0]
	s_nop 0
	v_pk_mul_f32 v[20:21], v[20:21], v[24:25]
	s_nop 0
	v_pk_mul_f32 v[20:21], v[22:23], v[20:21]
	s_nop 0
	v_pk_mul_f32 v[22:23], v[10:11], v[20:21]
	v_max_f32_e32 v20, 0, v10
	v_max_f32_e32 v21, 0, v11
	s_nop 0
	v_sub_f32_e64 v10, v20, |v22|
	v_cvt_pk_bf16_f32 v20, v12, v13
	s_nop 1
	v_sub_f32_e64 v11, v21, |v23|
	v_add_co_u32_e32 v24, vcc, s4, v152
	v_cvt_pk_bf16_f32 v21, v14, v15
	v_cvt_pk_bf16_f32 v22, v18, v19
	v_cvt_pk_bf16_f32 v23, v10, v11
	s_nop 1
	v_addc_co_u32_e32 v25, vcc, 0, v153, vcc
	global_store_dwordx4 v[24:25], v[20:23], off nt
	v_pk_mul_f32 v[24:25], v[4:5], v[4:5]
	s_nop 0
	v_pk_mul_f32 v[20:21], v[0:1], v[146:147] op_sel_hi:[1,0]
	v_fma_f32 v0, |v4|, s8, 1.0
	v_fma_f32 v1, |v5|, s8, 1.0
	v_pk_mul_f32 v[24:25], v[24:25], s[12:13] op_sel_hi:[1,0]
	v_rcp_f32_e32 v0, v0
	v_rcp_f32_e32 v1, v1
	v_exp_f32_e32 v24, v24
	v_exp_f32_e32 v25, v25
	v_pk_fma_f32 v[22:23], v[0:1], s[10:11], v[8:9] op_sel_hi:[1,0,0]
	s_nop 0
	v_pk_fma_f32 v[22:23], v[0:1], v[22:23], s[14:15] op_sel_hi:[1,1,0]
	s_nop 0
	v_pk_fma_f32 v[22:23], v[0:1], v[22:23], s[36:37] op_sel_hi:[1,1,0]
	s_nop 0
	v_pk_fma_f32 v[22:23], v[0:1], v[22:23], s[66:67] op_sel_hi:[1,1,0]
	s_nop 0
	v_pk_mul_f32 v[0:1], v[0:1], v[22:23]
	v_pk_mul_f32 v[22:23], v[6:7], v[6:7]
	v_pk_mul_f32 v[0:1], v[24:25], v[0:1]
	v_pk_mul_f32 v[22:23], v[22:23], s[12:13] op_sel_hi:[1,0]
	v_pk_mul_f32 v[24:25], v[4:5], v[0:1]
	v_max_f32_e32 v0, 0, v4
	v_max_f32_e32 v1, 0, v5
	v_sub_f32_e64 v0, v0, |v24|
	v_fma_f32 v4, |v6|, s8, 1.0
	v_fma_f32 v5, |v7|, s8, 1.0
	v_sub_f32_e64 v1, v1, |v25|
	v_rcp_f32_e32 v4, v4
	v_rcp_f32_e32 v5, v5
	v_exp_f32_e32 v22, v22
	v_exp_f32_e32 v23, v23
	v_pk_fma_f32 v[24:25], v[4:5], s[10:11], v[8:9] op_sel_hi:[1,0,0]
	s_nop 0
	v_pk_fma_f32 v[24:25], v[4:5], v[24:25], s[14:15] op_sel_hi:[1,1,0]
	s_nop 0
	v_pk_fma_f32 v[24:25], v[4:5], v[24:25], s[36:37] op_sel_hi:[1,1,0]
	s_nop 0
	v_pk_fma_f32 v[24:25], v[4:5], v[24:25], s[66:67] op_sel_hi:[1,1,0]
	s_nop 0
	v_pk_mul_f32 v[4:5], v[4:5], v[24:25]
	v_pk_mul_f32 v[24:25], v[20:21], v[20:21]
	v_pk_mul_f32 v[4:5], v[22:23], v[4:5]
	v_pk_mul_f32 v[24:25], v[24:25], s[12:13] op_sel_hi:[1,0]
	v_pk_mul_f32 v[22:23], v[6:7], v[4:5]
	v_max_f32_e32 v4, 0, v6
	v_max_f32_e32 v5, 0, v7
	v_sub_f32_e64 v4, v4, |v22|
	v_fma_f32 v6, |v20|, s8, 1.0
	v_fma_f32 v7, |v21|, s8, 1.0
	v_sub_f32_e64 v5, v5, |v23|
	v_rcp_f32_e32 v6, v6
	v_rcp_f32_e32 v7, v7
	v_exp_f32_e32 v24, v24
	v_exp_f32_e32 v25, v25
	v_pk_fma_f32 v[22:23], v[6:7], s[10:11], v[8:9] op_sel_hi:[1,0,0]
	s_nop 0
	v_pk_fma_f32 v[22:23], v[6:7], v[22:23], s[14:15] op_sel_hi:[1,1,0]
	s_nop 0
	v_pk_fma_f32 v[22:23], v[6:7], v[22:23], s[36:37] op_sel_hi:[1,1,0]
	s_nop 0
	v_pk_fma_f32 v[22:23], v[6:7], v[22:23], s[66:67] op_sel_hi:[1,1,0]
	s_nop 0
	v_pk_mul_f32 v[6:7], v[6:7], v[22:23]
	v_pk_mul_f32 v[22:23], v[2:3], v[2:3]
	v_pk_mul_f32 v[6:7], v[24:25], v[6:7]
	s_nop 0
	v_pk_mul_f32 v[24:25], v[20:21], v[6:7]
	v_max_f32_e32 v6, 0, v20
	v_max_f32_e32 v7, 0, v21
	v_sub_f32_e64 v6, v6, |v24|
	v_fma_f32 v20, |v2|, s8, 1.0
	v_fma_f32 v21, |v3|, s8, 1.0
	v_sub_f32_e64 v7, v7, |v25|
	v_rcp_f32_e32 v20, v20
	v_rcp_f32_e32 v21, v21
	s_nop 0
	v_pk_fma_f32 v[8:9], v[20:21], s[10:11], v[8:9] op_sel_hi:[1,0,0]
	s_nop 0
	v_pk_fma_f32 v[8:9], v[20:21], v[8:9], s[14:15] op_sel_hi:[1,1,0]
	s_nop 0
	v_pk_fma_f32 v[8:9], v[20:21], v[8:9], s[36:37] op_sel_hi:[1,1,0]
	s_nop 0
	v_pk_fma_f32 v[8:9], v[20:21], v[8:9], s[66:67] op_sel_hi:[1,1,0]
	s_nop 0
	v_pk_mul_f32 v[8:9], v[20:21], v[8:9]
	v_pk_mul_f32 v[20:21], v[22:23], s[12:13] op_sel_hi:[1,0]
	s_nop 0
	v_exp_f32_e32 v20, v20
	v_exp_f32_e32 v21, v21
	s_nop 0
	v_pk_mul_f32 v[8:9], v[20:21], v[8:9]
	s_nop 0
	v_pk_mul_f32 v[20:21], v[2:3], v[8:9]
	v_max_f32_e32 v8, 0, v2
	v_max_f32_e32 v9, 0, v3
	s_nop 0
	v_sub_f32_e64 v2, v8, |v20|
	v_cvt_pk_bf16_f32 v20, v0, v1
	s_nop 1
	v_sub_f32_e64 v3, v9, |v21|
	s_and_b64 vcc, exec, s[44:45]
	v_cvt_pk_bf16_f32 v21, v4, v5
	v_cvt_pk_bf16_f32 v22, v6, v7
	v_cvt_pk_bf16_f32 v23, v2, v3
	global_store_dwordx4 v[16:17], v[20:23], off offset:256 nt
	s_cbranch_vccnz .LBB0_89
	v_mul_f32_e32 v8, v11, v11
	v_mul_f32_e32 v1, v1, v1
	v_fmac_f32_e32 v8, v10, v10
	v_mul_f32_e32 v9, v13, v13
	v_mul_f32_e32 v10, v15, v15
	v_fmac_f32_e32 v1, v0, v0
	v_mul_f32_e32 v0, v5, v5
	v_fmac_f32_e32 v9, v12, v12
	v_fmac_f32_e32 v10, v14, v14
	v_fmac_f32_e32 v0, v4, v4
	v_add_f32_e32 v9, v9, v10
	v_mul_f32_e32 v10, v19, v19
	v_add_f32_e32 v0, v1, v0
	v_mul_f32_e32 v1, v7, v7
	v_fmac_f32_e32 v10, v18, v18
	v_mul_f32_e32 v3, v3, v3
	v_fmac_f32_e32 v1, v6, v6
	v_add_f32_e32 v9, v10, v9
	v_fmac_f32_e32 v3, v2, v2
	v_add_f32_e32 v0, v1, v0
	v_add_f32_e32 v8, v8, v9
	v_add_f32_e32 v0, v3, v0
	v_add_f32_e32 v0, v8, v0
	ds_bpermute_b32 v1, v147, v0
	s_waitcnt lgkmcnt(0)
	v_add_f32_e32 v0, v0, v1
	ds_bpermute_b32 v1, v165, v0
	s_and_saveexec_b64 s[26:27], s[40:41]
	s_cbranch_execz .LBB0_88
	s_waitcnt lgkmcnt(0)
	v_add_f32_e32 v0, v0, v1
	v_mul_f32_e32 v0, 0x4b800000, v0
	v_trunc_f32_e32 v0, v0
	v_mul_f32_e32 v1, 0x2f800000, v0
	v_floor_f32_e32 v1, v1
	v_fmac_f32_e32 v0, 0xcf800000, v1
	v_cvt_u32_f32_e32 v0, v0
	v_cvt_u32_f32_e32 v1, v1
	v_lshl_add_u64 v[2:3], v[142:143], 3, s[52:53]
	global_atomic_add_x2 v[2:3], v[0:1], off offset:1408
